# pool-branch weight fold: stage the wave-uniform w_branch rows and pool_scale through LDS (4 coalesced loads + broadcast ds_reads) instead of 288 uniform-address vector loads per item
# speedup vs baseline: 1.0293x; 1.0293x over previous
; #define ARG_IN(i) argp(i)
; __device__ __forceinline__ void weights_phase(int l, LAS unsigned char* lds, int vcu, int G, int wave, int lane) {
;     ...
;             const int cblk = r & 127, kh = (r >> 7) & 1, g = r >> 8, ci = kh * 64 + lane;
;             const float* wp = ARG_IN(12) + ((size_t)(l * 4 + g) * 128 + ci) * 128; const float* ps = ARG_IN(13) + l * 512 + g * 128;
;             const float* wb = ARG_IN(14) + ((size_t)(l * 3 + 1) * 512 + g * 128) * 1024 + cblk * 8;
;             f32x4 a0 = {0.f, 0.f, 0.f, 0.f}, a1 = {0.f, 0.f, 0.f, 0.f};
; #pragma unroll 16
;             for (int e = 0; e < 128; ++e) { const float cf = wp[e] * ps[e]; a0 += cf * *(const f32x4*)(wb + (size_t)e * 1024); a1 += cf * *(const f32x4*)(wb + (size_t)e * 1024 + 4); }
.LBB0_125:
	v_mbcnt_lo_u32_b32 v0, -1, 0
	v_mbcnt_hi_u32_b32 v0, -1, v0
	v_readlane_b32 s20, v255, 4
	v_lshrrev_b32_e32 v3, 1, v0
	v_lshlrev_b32_e32 v3, 12, v3
	v_and_b32_e32 v2, 1, v0
	v_lshl_or_b32 v2, v2, 4, v3
	s_lshl_b32 s20, s20, 14
	v_lshlrev_b32_e32 v4, 3, v0
	s_add_u32 s14, s6, 0x200000
	s_addc_u32 s15, s54, 0
	global_load_dwordx4 v[10:13], v2, s[14:15]
	s_add_u32 s14, s14, 0x20000
	s_addc_u32 s15, s15, 0
	global_load_dwordx4 v[14:17], v2, s[14:15]
	s_add_u32 s14, s14, 0x20000
	s_addc_u32 s15, s15, 0
	global_load_dwordx4 v[18:21], v2, s[14:15]
	s_add_u32 s14, s14, 0x20000
	s_addc_u32 s15, s15, 0
	global_load_dwordx4 v[22:25], v2, s[14:15]
	global_load_dwordx2 v[26:27], v4, s[0:1]
	v_lshl_add_u32 v1, v0, 4, s20
	v_lshl_add_u32 v5, v0, 3, s20
	v_mov_b32_e32 v6, s20
	v_add_u32_e32 v47, 0x1000, v6
	v_mov_b32_e32 v8, v66
	v_mov_b32_e32 v9, v67
	s_waitcnt vmcnt(0)
	ds_write_b128 v1, v[10:13]
	ds_write_b128 v1, v[14:17] offset:1024
	ds_write_b128 v1, v[18:21] offset:2048
	ds_write_b128 v1, v[22:25] offset:3072
	ds_write_b64 v5, v[26:27] offset:4096
	s_mov_b32 s21, 0
	s_waitcnt lgkmcnt(0)
.Lweff_half_a:
	global_load_dwordx4 v[114:117], v[8:9], off
	global_load_dwordx4 v[118:121], v[8:9], off offset:16
	global_load_dwordx4 v[122:125], v[8:9], off offset:32
	global_load_dwordx4 v[126:129], v[8:9], off offset:48
	global_load_dwordx4 v[130:133], v[8:9], off offset:64
	global_load_dwordx4 v[134:137], v[8:9], off offset:80
	global_load_dwordx4 v[138:141], v[8:9], off offset:96
	global_load_dwordx4 v[142:145], v[8:9], off offset:112
	global_load_dwordx4 v[146:149], v[8:9], off offset:128
	global_load_dwordx4 v[150:153], v[8:9], off offset:144
	global_load_dwordx4 v[154:157], v[8:9], off offset:160
	global_load_dwordx4 v[158:161], v[8:9], off offset:176
	global_load_dwordx4 v[162:165], v[8:9], off offset:192
	global_load_dwordx4 v[166:169], v[8:9], off offset:208
	global_load_dwordx4 v[170:173], v[8:9], off offset:224
	global_load_dwordx4 v[174:177], v[8:9], off offset:240
	s_waitcnt vmcnt(0)
	ds_read_b128 v[28:31], v6
	ds_read_b128 v[32:35], v6 offset:16
	ds_read_b32 v36, v47
	ds_read_b128 v[38:41], v6 offset:32
	ds_read_b128 v[42:45], v6 offset:48
	ds_read_b32 v46, v47 offset:4
	s_waitcnt lgkmcnt(0)
	v_mul_f32_e32 v7, v114, v36
	v_fmac_f32_e32 v68, v28, v7
	v_fmac_f32_e32 v69, v29, v7
	v_fmac_f32_e32 v70, v30, v7
	v_fmac_f32_e32 v71, v31, v7
	v_fmac_f32_e32 v74, v32, v7
	v_fmac_f32_e32 v75, v33, v7
	v_fmac_f32_e32 v72, v34, v7
	v_fmac_f32_e32 v73, v35, v7
	v_mul_f32_e32 v7, v115, v46
	v_fmac_f32_e32 v68, v38, v7
	v_fmac_f32_e32 v69, v39, v7
	v_fmac_f32_e32 v70, v40, v7
	v_fmac_f32_e32 v71, v41, v7
	v_fmac_f32_e32 v74, v42, v7
	v_fmac_f32_e32 v75, v43, v7
	v_fmac_f32_e32 v72, v44, v7
	v_fmac_f32_e32 v73, v45, v7
	ds_read_b128 v[28:31], v6 offset:64
	ds_read_b128 v[32:35], v6 offset:80
	ds_read_b32 v36, v47 offset:8
	ds_read_b128 v[38:41], v6 offset:96
	ds_read_b128 v[42:45], v6 offset:112
	ds_read_b32 v46, v47 offset:12
	s_waitcnt lgkmcnt(0)
	v_mul_f32_e32 v7, v116, v36
	v_fmac_f32_e32 v68, v28, v7
	v_fmac_f32_e32 v69, v29, v7
	v_fmac_f32_e32 v70, v30, v7
	v_fmac_f32_e32 v71, v31, v7
	v_fmac_f32_e32 v74, v32, v7
	v_fmac_f32_e32 v75, v33, v7
	v_fmac_f32_e32 v72, v34, v7
	v_fmac_f32_e32 v73, v35, v7
	v_mul_f32_e32 v7, v117, v46
	v_fmac_f32_e32 v68, v38, v7
	v_fmac_f32_e32 v69, v39, v7
	v_fmac_f32_e32 v70, v40, v7
	v_fmac_f32_e32 v71, v41, v7
	v_fmac_f32_e32 v74, v42, v7
	v_fmac_f32_e32 v75, v43, v7
	v_fmac_f32_e32 v72, v44, v7
	v_fmac_f32_e32 v73, v45, v7
	ds_read_b128 v[28:31], v6 offset:128
	ds_read_b128 v[32:35], v6 offset:144
	ds_read_b32 v36, v47 offset:16
	ds_read_b128 v[38:41], v6 offset:160
	ds_read_b128 v[42:45], v6 offset:176
	ds_read_b32 v46, v47 offset:20
	s_waitcnt lgkmcnt(0)
	v_mul_f32_e32 v7, v118, v36
	v_fmac_f32_e32 v68, v28, v7
	v_fmac_f32_e32 v69, v29, v7
	v_fmac_f32_e32 v70, v30, v7
	v_fmac_f32_e32 v71, v31, v7
	v_fmac_f32_e32 v74, v32, v7
	v_fmac_f32_e32 v75, v33, v7
	v_fmac_f32_e32 v72, v34, v7
	v_fmac_f32_e32 v73, v35, v7
	v_mul_f32_e32 v7, v119, v46
	v_fmac_f32_e32 v68, v38, v7
	v_fmac_f32_e32 v69, v39, v7
	v_fmac_f32_e32 v70, v40, v7
	v_fmac_f32_e32 v71, v41, v7
	v_fmac_f32_e32 v74, v42, v7
	v_fmac_f32_e32 v75, v43, v7
	v_fmac_f32_e32 v72, v44, v7
	v_fmac_f32_e32 v73, v45, v7
	ds_read_b128 v[28:31], v6 offset:192
	ds_read_b128 v[32:35], v6 offset:208
	ds_read_b32 v36, v47 offset:24
	ds_read_b128 v[38:41], v6 offset:224
	ds_read_b128 v[42:45], v6 offset:240
	ds_read_b32 v46, v47 offset:28
	s_waitcnt lgkmcnt(0)
	v_mul_f32_e32 v7, v120, v36
	v_fmac_f32_e32 v68, v28, v7
	v_fmac_f32_e32 v69, v29, v7
	v_fmac_f32_e32 v70, v30, v7
	v_fmac_f32_e32 v71, v31, v7
	v_fmac_f32_e32 v74, v32, v7
	v_fmac_f32_e32 v75, v33, v7
	v_fmac_f32_e32 v72, v34, v7
	v_fmac_f32_e32 v73, v35, v7
	v_mul_f32_e32 v7, v121, v46
	v_fmac_f32_e32 v68, v38, v7
	v_fmac_f32_e32 v69, v39, v7
	v_fmac_f32_e32 v70, v40, v7
	v_fmac_f32_e32 v71, v41, v7
	v_fmac_f32_e32 v74, v42, v7
	v_fmac_f32_e32 v75, v43, v7
	v_fmac_f32_e32 v72, v44, v7
	v_fmac_f32_e32 v73, v45, v7
	ds_read_b128 v[28:31], v6 offset:256
	ds_read_b128 v[32:35], v6 offset:272
	ds_read_b32 v36, v47 offset:32
	ds_read_b128 v[38:41], v6 offset:288
	ds_read_b128 v[42:45], v6 offset:304
	ds_read_b32 v46, v47 offset:36
	s_waitcnt lgkmcnt(0)
; __device__ __forceinline__ void weights_phase(int l, LAS unsigned char* lds, int vcu, int G, int wave, int lane) {
;     ...
; #pragma unroll 16
;             for (int e = 0; e < 128; ++e) { const float cf = wp[e] * ps[e]; a0 += cf * *(const f32x4*)(wb + (size_t)e * 1024); a1 += cf * *(const f32x4*)(wb + (size_t)e * 1024 + 4); }
	v_mul_f32_e32 v7, v122, v36
	v_fmac_f32_e32 v68, v28, v7
	v_fmac_f32_e32 v69, v29, v7
	v_fmac_f32_e32 v70, v30, v7
	v_fmac_f32_e32 v71, v31, v7
	v_fmac_f32_e32 v74, v32, v7
	v_fmac_f32_e32 v75, v33, v7
	v_fmac_f32_e32 v72, v34, v7
	v_fmac_f32_e32 v73, v35, v7
	v_mul_f32_e32 v7, v123, v46
	v_fmac_f32_e32 v68, v38, v7
	v_fmac_f32_e32 v69, v39, v7
	v_fmac_f32_e32 v70, v40, v7
	v_fmac_f32_e32 v71, v41, v7
	v_fmac_f32_e32 v74, v42, v7
	v_fmac_f32_e32 v75, v43, v7
	v_fmac_f32_e32 v72, v44, v7
	v_fmac_f32_e32 v73, v45, v7
	ds_read_b128 v[28:31], v6 offset:320
	ds_read_b128 v[32:35], v6 offset:336
	ds_read_b32 v36, v47 offset:40
	ds_read_b128 v[38:41], v6 offset:352
	ds_read_b128 v[42:45], v6 offset:368
	ds_read_b32 v46, v47 offset:44
	s_waitcnt lgkmcnt(0)
	v_mul_f32_e32 v7, v124, v36
	v_fmac_f32_e32 v68, v28, v7
	v_fmac_f32_e32 v69, v29, v7
	v_fmac_f32_e32 v70, v30, v7
	v_fmac_f32_e32 v71, v31, v7
	v_fmac_f32_e32 v74, v32, v7
	v_fmac_f32_e32 v75, v33, v7
	v_fmac_f32_e32 v72, v34, v7
	v_fmac_f32_e32 v73, v35, v7
	v_mul_f32_e32 v7, v125, v46
	v_fmac_f32_e32 v68, v38, v7
	v_fmac_f32_e32 v69, v39, v7
	v_fmac_f32_e32 v70, v40, v7
	v_fmac_f32_e32 v71, v41, v7
	v_fmac_f32_e32 v74, v42, v7
	v_fmac_f32_e32 v75, v43, v7
	v_fmac_f32_e32 v72, v44, v7
	v_fmac_f32_e32 v73, v45, v7
	ds_read_b128 v[28:31], v6 offset:384
	ds_read_b128 v[32:35], v6 offset:400
	ds_read_b32 v36, v47 offset:48
	ds_read_b128 v[38:41], v6 offset:416
	ds_read_b128 v[42:45], v6 offset:432
	ds_read_b32 v46, v47 offset:52
	s_waitcnt lgkmcnt(0)
	v_mul_f32_e32 v7, v126, v36
	v_fmac_f32_e32 v68, v28, v7
	v_fmac_f32_e32 v69, v29, v7
	v_fmac_f32_e32 v70, v30, v7
	v_fmac_f32_e32 v71, v31, v7
	v_fmac_f32_e32 v74, v32, v7
	v_fmac_f32_e32 v75, v33, v7
	v_fmac_f32_e32 v72, v34, v7
	v_fmac_f32_e32 v73, v35, v7
	v_mul_f32_e32 v7, v127, v46
	v_fmac_f32_e32 v68, v38, v7
	v_fmac_f32_e32 v69, v39, v7
	v_fmac_f32_e32 v70, v40, v7
	v_fmac_f32_e32 v71, v41, v7
	v_fmac_f32_e32 v74, v42, v7
	v_fmac_f32_e32 v75, v43, v7
	v_fmac_f32_e32 v72, v44, v7
	v_fmac_f32_e32 v73, v45, v7
	ds_read_b128 v[28:31], v6 offset:448
	ds_read_b128 v[32:35], v6 offset:464
	ds_read_b32 v36, v47 offset:56
	ds_read_b128 v[38:41], v6 offset:480
	ds_read_b128 v[42:45], v6 offset:496
	ds_read_b32 v46, v47 offset:60
	s_waitcnt lgkmcnt(0)
	v_mul_f32_e32 v7, v128, v36
	v_fmac_f32_e32 v68, v28, v7
	v_fmac_f32_e32 v69, v29, v7
	v_fmac_f32_e32 v70, v30, v7
	v_fmac_f32_e32 v71, v31, v7
	v_fmac_f32_e32 v74, v32, v7
	v_fmac_f32_e32 v75, v33, v7
	v_fmac_f32_e32 v72, v34, v7
	v_fmac_f32_e32 v73, v35, v7
	v_mul_f32_e32 v7, v129, v46
	v_fmac_f32_e32 v68, v38, v7
	v_fmac_f32_e32 v69, v39, v7
	v_fmac_f32_e32 v70, v40, v7
	v_fmac_f32_e32 v71, v41, v7
	v_fmac_f32_e32 v74, v42, v7
	v_fmac_f32_e32 v75, v43, v7
	v_fmac_f32_e32 v72, v44, v7
	v_fmac_f32_e32 v73, v45, v7
	ds_read_b128 v[28:31], v6 offset:512
	ds_read_b128 v[32:35], v6 offset:528
	ds_read_b32 v36, v47 offset:64
	ds_read_b128 v[38:41], v6 offset:544
	ds_read_b128 v[42:45], v6 offset:560
	ds_read_b32 v46, v47 offset:68
	s_waitcnt lgkmcnt(0)
	v_mul_f32_e32 v7, v130, v36
	v_fmac_f32_e32 v68, v28, v7
	v_fmac_f32_e32 v69, v29, v7
	v_fmac_f32_e32 v70, v30, v7
	v_fmac_f32_e32 v71, v31, v7
	v_fmac_f32_e32 v74, v32, v7
	v_fmac_f32_e32 v75, v33, v7
	v_fmac_f32_e32 v72, v34, v7
	v_fmac_f32_e32 v73, v35, v7
	v_mul_f32_e32 v7, v131, v46
	v_fmac_f32_e32 v68, v38, v7
	v_fmac_f32_e32 v69, v39, v7
	v_fmac_f32_e32 v70, v40, v7
	v_fmac_f32_e32 v71, v41, v7
	v_fmac_f32_e32 v74, v42, v7
	v_fmac_f32_e32 v75, v43, v7
	v_fmac_f32_e32 v72, v44, v7
	v_fmac_f32_e32 v73, v45, v7
	ds_read_b128 v[28:31], v6 offset:576
	ds_read_b128 v[32:35], v6 offset:592
	ds_read_b32 v36, v47 offset:72
	ds_read_b128 v[38:41], v6 offset:608
	ds_read_b128 v[42:45], v6 offset:624
	ds_read_b32 v46, v47 offset:76
	s_waitcnt lgkmcnt(0)
	v_mul_f32_e32 v7, v132, v36
	v_fmac_f32_e32 v68, v28, v7
	v_fmac_f32_e32 v69, v29, v7
	v_fmac_f32_e32 v70, v30, v7
	v_fmac_f32_e32 v71, v31, v7
	v_fmac_f32_e32 v74, v32, v7
	v_fmac_f32_e32 v75, v33, v7
	v_fmac_f32_e32 v72, v34, v7
	v_fmac_f32_e32 v73, v35, v7
	v_mul_f32_e32 v7, v133, v46
	v_fmac_f32_e32 v68, v38, v7
	v_fmac_f32_e32 v69, v39, v7
	v_fmac_f32_e32 v70, v40, v7
	v_fmac_f32_e32 v71, v41, v7
	v_fmac_f32_e32 v74, v42, v7
	v_fmac_f32_e32 v75, v43, v7
	v_fmac_f32_e32 v72, v44, v7
	v_fmac_f32_e32 v73, v45, v7
	ds_read_b128 v[28:31], v6 offset:640
	ds_read_b128 v[32:35], v6 offset:656
	ds_read_b32 v36, v47 offset:80
	ds_read_b128 v[38:41], v6 offset:672
	ds_read_b128 v[42:45], v6 offset:688
	ds_read_b32 v46, v47 offset:84
	s_waitcnt lgkmcnt(0)
	v_mul_f32_e32 v7, v134, v36
	v_fmac_f32_e32 v68, v28, v7
	v_fmac_f32_e32 v69, v29, v7
	v_fmac_f32_e32 v70, v30, v7
	v_fmac_f32_e32 v71, v31, v7
	v_fmac_f32_e32 v74, v32, v7
	v_fmac_f32_e32 v75, v33, v7
	v_fmac_f32_e32 v72, v34, v7
	v_fmac_f32_e32 v73, v35, v7
	v_mul_f32_e32 v7, v135, v46
	v_fmac_f32_e32 v68, v38, v7
	v_fmac_f32_e32 v69, v39, v7
	v_fmac_f32_e32 v70, v40, v7
	v_fmac_f32_e32 v71, v41, v7
	v_fmac_f32_e32 v74, v42, v7
	v_fmac_f32_e32 v75, v43, v7
	v_fmac_f32_e32 v72, v44, v7
	v_fmac_f32_e32 v73, v45, v7
	ds_read_b128 v[28:31], v6 offset:704
	ds_read_b128 v[32:35], v6 offset:720
	ds_read_b32 v36, v47 offset:88
	ds_read_b128 v[38:41], v6 offset:736
	ds_read_b128 v[42:45], v6 offset:752
	ds_read_b32 v46, v47 offset:92
	s_waitcnt lgkmcnt(0)
; __device__ __forceinline__ void weights_phase(int l, LAS unsigned char* lds, int vcu, int G, int wave, int lane) {
;     ...
; #pragma unroll 16
;             for (int e = 0; e < 128; ++e) { const float cf = wp[e] * ps[e]; a0 += cf * *(const f32x4*)(wb + (size_t)e * 1024); a1 += cf * *(const f32x4*)(wb + (size_t)e * 1024 + 4); }
	v_mul_f32_e32 v7, v136, v36
	v_fmac_f32_e32 v68, v28, v7
	v_fmac_f32_e32 v69, v29, v7
	v_fmac_f32_e32 v70, v30, v7
	v_fmac_f32_e32 v71, v31, v7
	v_fmac_f32_e32 v74, v32, v7
	v_fmac_f32_e32 v75, v33, v7
	v_fmac_f32_e32 v72, v34, v7
	v_fmac_f32_e32 v73, v35, v7
	v_mul_f32_e32 v7, v137, v46
	v_fmac_f32_e32 v68, v38, v7
	v_fmac_f32_e32 v69, v39, v7
	v_fmac_f32_e32 v70, v40, v7
	v_fmac_f32_e32 v71, v41, v7
	v_fmac_f32_e32 v74, v42, v7
	v_fmac_f32_e32 v75, v43, v7
	v_fmac_f32_e32 v72, v44, v7
	v_fmac_f32_e32 v73, v45, v7
	ds_read_b128 v[28:31], v6 offset:768
	ds_read_b128 v[32:35], v6 offset:784
	ds_read_b32 v36, v47 offset:96
	ds_read_b128 v[38:41], v6 offset:800
	ds_read_b128 v[42:45], v6 offset:816
	ds_read_b32 v46, v47 offset:100
	s_waitcnt lgkmcnt(0)
	v_mul_f32_e32 v7, v138, v36
	v_fmac_f32_e32 v68, v28, v7
	v_fmac_f32_e32 v69, v29, v7
	v_fmac_f32_e32 v70, v30, v7
	v_fmac_f32_e32 v71, v31, v7
	v_fmac_f32_e32 v74, v32, v7
	v_fmac_f32_e32 v75, v33, v7
	v_fmac_f32_e32 v72, v34, v7
	v_fmac_f32_e32 v73, v35, v7
	v_mul_f32_e32 v7, v139, v46
	v_fmac_f32_e32 v68, v38, v7
	v_fmac_f32_e32 v69, v39, v7
	v_fmac_f32_e32 v70, v40, v7
	v_fmac_f32_e32 v71, v41, v7
	v_fmac_f32_e32 v74, v42, v7
	v_fmac_f32_e32 v75, v43, v7
	v_fmac_f32_e32 v72, v44, v7
	v_fmac_f32_e32 v73, v45, v7
	ds_read_b128 v[28:31], v6 offset:832
	ds_read_b128 v[32:35], v6 offset:848
	ds_read_b32 v36, v47 offset:104
	ds_read_b128 v[38:41], v6 offset:864
	ds_read_b128 v[42:45], v6 offset:880
	ds_read_b32 v46, v47 offset:108
	s_waitcnt lgkmcnt(0)
	v_mul_f32_e32 v7, v140, v36
	v_fmac_f32_e32 v68, v28, v7
	v_fmac_f32_e32 v69, v29, v7
	v_fmac_f32_e32 v70, v30, v7
	v_fmac_f32_e32 v71, v31, v7
	v_fmac_f32_e32 v74, v32, v7
	v_fmac_f32_e32 v75, v33, v7
	v_fmac_f32_e32 v72, v34, v7
	v_fmac_f32_e32 v73, v35, v7
	v_mul_f32_e32 v7, v141, v46
	v_fmac_f32_e32 v68, v38, v7
	v_fmac_f32_e32 v69, v39, v7
	v_fmac_f32_e32 v70, v40, v7
	v_fmac_f32_e32 v71, v41, v7
	v_fmac_f32_e32 v74, v42, v7
	v_fmac_f32_e32 v75, v43, v7
	v_fmac_f32_e32 v72, v44, v7
	v_fmac_f32_e32 v73, v45, v7
	ds_read_b128 v[28:31], v6 offset:896
	ds_read_b128 v[32:35], v6 offset:912
	ds_read_b32 v36, v47 offset:112
	ds_read_b128 v[38:41], v6 offset:928
	ds_read_b128 v[42:45], v6 offset:944
	ds_read_b32 v46, v47 offset:116
	s_waitcnt lgkmcnt(0)
	v_mul_f32_e32 v7, v142, v36
	v_fmac_f32_e32 v68, v28, v7
	v_fmac_f32_e32 v69, v29, v7
	v_fmac_f32_e32 v70, v30, v7
	v_fmac_f32_e32 v71, v31, v7
	v_fmac_f32_e32 v74, v32, v7
	v_fmac_f32_e32 v75, v33, v7
	v_fmac_f32_e32 v72, v34, v7
	v_fmac_f32_e32 v73, v35, v7
	v_mul_f32_e32 v7, v143, v46
	v_fmac_f32_e32 v68, v38, v7
	v_fmac_f32_e32 v69, v39, v7
	v_fmac_f32_e32 v70, v40, v7
	v_fmac_f32_e32 v71, v41, v7
	v_fmac_f32_e32 v74, v42, v7
	v_fmac_f32_e32 v75, v43, v7
	v_fmac_f32_e32 v72, v44, v7
	v_fmac_f32_e32 v73, v45, v7
	ds_read_b128 v[28:31], v6 offset:960
	ds_read_b128 v[32:35], v6 offset:976
	ds_read_b32 v36, v47 offset:120
	ds_read_b128 v[38:41], v6 offset:992
	ds_read_b128 v[42:45], v6 offset:1008
	ds_read_b32 v46, v47 offset:124
	s_waitcnt lgkmcnt(0)
	v_mul_f32_e32 v7, v144, v36
	v_fmac_f32_e32 v68, v28, v7
	v_fmac_f32_e32 v69, v29, v7
	v_fmac_f32_e32 v70, v30, v7
	v_fmac_f32_e32 v71, v31, v7
	v_fmac_f32_e32 v74, v32, v7
	v_fmac_f32_e32 v75, v33, v7
	v_fmac_f32_e32 v72, v34, v7
	v_fmac_f32_e32 v73, v35, v7
	v_mul_f32_e32 v7, v145, v46
	v_fmac_f32_e32 v68, v38, v7
	v_fmac_f32_e32 v69, v39, v7
	v_fmac_f32_e32 v70, v40, v7
	v_fmac_f32_e32 v71, v41, v7
	v_fmac_f32_e32 v74, v42, v7
	v_fmac_f32_e32 v75, v43, v7
	v_fmac_f32_e32 v72, v44, v7
	v_fmac_f32_e32 v73, v45, v7
	ds_read_b128 v[28:31], v6 offset:1024
	ds_read_b128 v[32:35], v6 offset:1040
	ds_read_b32 v36, v47 offset:128
	ds_read_b128 v[38:41], v6 offset:1056
	ds_read_b128 v[42:45], v6 offset:1072
	ds_read_b32 v46, v47 offset:132
	s_waitcnt lgkmcnt(0)
	v_mul_f32_e32 v7, v146, v36
	v_fmac_f32_e32 v68, v28, v7
	v_fmac_f32_e32 v69, v29, v7
	v_fmac_f32_e32 v70, v30, v7
	v_fmac_f32_e32 v71, v31, v7
	v_fmac_f32_e32 v74, v32, v7
	v_fmac_f32_e32 v75, v33, v7
	v_fmac_f32_e32 v72, v34, v7
	v_fmac_f32_e32 v73, v35, v7
	v_mul_f32_e32 v7, v147, v46
	v_fmac_f32_e32 v68, v38, v7
	v_fmac_f32_e32 v69, v39, v7
	v_fmac_f32_e32 v70, v40, v7
	v_fmac_f32_e32 v71, v41, v7
	v_fmac_f32_e32 v74, v42, v7
	v_fmac_f32_e32 v75, v43, v7
	v_fmac_f32_e32 v72, v44, v7
	v_fmac_f32_e32 v73, v45, v7
	ds_read_b128 v[28:31], v6 offset:1088
	ds_read_b128 v[32:35], v6 offset:1104
	ds_read_b32 v36, v47 offset:136
	ds_read_b128 v[38:41], v6 offset:1120
	ds_read_b128 v[42:45], v6 offset:1136
	ds_read_b32 v46, v47 offset:140
	s_waitcnt lgkmcnt(0)
	v_mul_f32_e32 v7, v148, v36
	v_fmac_f32_e32 v68, v28, v7
	v_fmac_f32_e32 v69, v29, v7
	v_fmac_f32_e32 v70, v30, v7
	v_fmac_f32_e32 v71, v31, v7
	v_fmac_f32_e32 v74, v32, v7
	v_fmac_f32_e32 v75, v33, v7
	v_fmac_f32_e32 v72, v34, v7
	v_fmac_f32_e32 v73, v35, v7
	v_mul_f32_e32 v7, v149, v46
	v_fmac_f32_e32 v68, v38, v7
	v_fmac_f32_e32 v69, v39, v7
	v_fmac_f32_e32 v70, v40, v7
	v_fmac_f32_e32 v71, v41, v7
	v_fmac_f32_e32 v74, v42, v7
	v_fmac_f32_e32 v75, v43, v7
	v_fmac_f32_e32 v72, v44, v7
	v_fmac_f32_e32 v73, v45, v7
	ds_read_b128 v[28:31], v6 offset:1152
	ds_read_b128 v[32:35], v6 offset:1168
	ds_read_b32 v36, v47 offset:144
	ds_read_b128 v[38:41], v6 offset:1184
	ds_read_b128 v[42:45], v6 offset:1200
	ds_read_b32 v46, v47 offset:148
	s_waitcnt lgkmcnt(0)
; __device__ __forceinline__ void weights_phase(int l, LAS unsigned char* lds, int vcu, int G, int wave, int lane) {
;     ...
; #pragma unroll 16
;             for (int e = 0; e < 128; ++e) { const float cf = wp[e] * ps[e]; a0 += cf * *(const f32x4*)(wb + (size_t)e * 1024); a1 += cf * *(const f32x4*)(wb + (size_t)e * 1024 + 4); }
	v_mul_f32_e32 v7, v150, v36
	v_fmac_f32_e32 v68, v28, v7
	v_fmac_f32_e32 v69, v29, v7
	v_fmac_f32_e32 v70, v30, v7
	v_fmac_f32_e32 v71, v31, v7
	v_fmac_f32_e32 v74, v32, v7
	v_fmac_f32_e32 v75, v33, v7
	v_fmac_f32_e32 v72, v34, v7
	v_fmac_f32_e32 v73, v35, v7
	v_mul_f32_e32 v7, v151, v46
	v_fmac_f32_e32 v68, v38, v7
	v_fmac_f32_e32 v69, v39, v7
	v_fmac_f32_e32 v70, v40, v7
	v_fmac_f32_e32 v71, v41, v7
	v_fmac_f32_e32 v74, v42, v7
	v_fmac_f32_e32 v75, v43, v7
	v_fmac_f32_e32 v72, v44, v7
	v_fmac_f32_e32 v73, v45, v7
	ds_read_b128 v[28:31], v6 offset:1216
	ds_read_b128 v[32:35], v6 offset:1232
	ds_read_b32 v36, v47 offset:152
	ds_read_b128 v[38:41], v6 offset:1248
	ds_read_b128 v[42:45], v6 offset:1264
	ds_read_b32 v46, v47 offset:156
	s_waitcnt lgkmcnt(0)
	v_mul_f32_e32 v7, v152, v36
	v_fmac_f32_e32 v68, v28, v7
	v_fmac_f32_e32 v69, v29, v7
	v_fmac_f32_e32 v70, v30, v7
	v_fmac_f32_e32 v71, v31, v7
	v_fmac_f32_e32 v74, v32, v7
	v_fmac_f32_e32 v75, v33, v7
	v_fmac_f32_e32 v72, v34, v7
	v_fmac_f32_e32 v73, v35, v7
	v_mul_f32_e32 v7, v153, v46
	v_fmac_f32_e32 v68, v38, v7
	v_fmac_f32_e32 v69, v39, v7
	v_fmac_f32_e32 v70, v40, v7
	v_fmac_f32_e32 v71, v41, v7
	v_fmac_f32_e32 v74, v42, v7
	v_fmac_f32_e32 v75, v43, v7
	v_fmac_f32_e32 v72, v44, v7
	v_fmac_f32_e32 v73, v45, v7
	ds_read_b128 v[28:31], v6 offset:1280
	ds_read_b128 v[32:35], v6 offset:1296
	ds_read_b32 v36, v47 offset:160
	ds_read_b128 v[38:41], v6 offset:1312
	ds_read_b128 v[42:45], v6 offset:1328
	ds_read_b32 v46, v47 offset:164
	s_waitcnt lgkmcnt(0)
	v_mul_f32_e32 v7, v154, v36
	v_fmac_f32_e32 v68, v28, v7
	v_fmac_f32_e32 v69, v29, v7
	v_fmac_f32_e32 v70, v30, v7
	v_fmac_f32_e32 v71, v31, v7
	v_fmac_f32_e32 v74, v32, v7
	v_fmac_f32_e32 v75, v33, v7
	v_fmac_f32_e32 v72, v34, v7
	v_fmac_f32_e32 v73, v35, v7
	v_mul_f32_e32 v7, v155, v46
	v_fmac_f32_e32 v68, v38, v7
	v_fmac_f32_e32 v69, v39, v7
	v_fmac_f32_e32 v70, v40, v7
	v_fmac_f32_e32 v71, v41, v7
	v_fmac_f32_e32 v74, v42, v7
	v_fmac_f32_e32 v75, v43, v7
	v_fmac_f32_e32 v72, v44, v7
	v_fmac_f32_e32 v73, v45, v7
	ds_read_b128 v[28:31], v6 offset:1344
	ds_read_b128 v[32:35], v6 offset:1360
	ds_read_b32 v36, v47 offset:168
	ds_read_b128 v[38:41], v6 offset:1376
	ds_read_b128 v[42:45], v6 offset:1392
	ds_read_b32 v46, v47 offset:172
	s_waitcnt lgkmcnt(0)
	v_mul_f32_e32 v7, v156, v36
	v_fmac_f32_e32 v68, v28, v7
	v_fmac_f32_e32 v69, v29, v7
	v_fmac_f32_e32 v70, v30, v7
	v_fmac_f32_e32 v71, v31, v7
	v_fmac_f32_e32 v74, v32, v7
	v_fmac_f32_e32 v75, v33, v7
	v_fmac_f32_e32 v72, v34, v7
	v_fmac_f32_e32 v73, v35, v7
	v_mul_f32_e32 v7, v157, v46
	v_fmac_f32_e32 v68, v38, v7
	v_fmac_f32_e32 v69, v39, v7
	v_fmac_f32_e32 v70, v40, v7
	v_fmac_f32_e32 v71, v41, v7
	v_fmac_f32_e32 v74, v42, v7
	v_fmac_f32_e32 v75, v43, v7
	v_fmac_f32_e32 v72, v44, v7
	v_fmac_f32_e32 v73, v45, v7
	ds_read_b128 v[28:31], v6 offset:1408
	ds_read_b128 v[32:35], v6 offset:1424
	ds_read_b32 v36, v47 offset:176
	ds_read_b128 v[38:41], v6 offset:1440
	ds_read_b128 v[42:45], v6 offset:1456
	ds_read_b32 v46, v47 offset:180
	s_waitcnt lgkmcnt(0)
	v_mul_f32_e32 v7, v158, v36
	v_fmac_f32_e32 v68, v28, v7
	v_fmac_f32_e32 v69, v29, v7
	v_fmac_f32_e32 v70, v30, v7
	v_fmac_f32_e32 v71, v31, v7
	v_fmac_f32_e32 v74, v32, v7
	v_fmac_f32_e32 v75, v33, v7
	v_fmac_f32_e32 v72, v34, v7
	v_fmac_f32_e32 v73, v35, v7
	v_mul_f32_e32 v7, v159, v46
	v_fmac_f32_e32 v68, v38, v7
	v_fmac_f32_e32 v69, v39, v7
	v_fmac_f32_e32 v70, v40, v7
	v_fmac_f32_e32 v71, v41, v7
	v_fmac_f32_e32 v74, v42, v7
	v_fmac_f32_e32 v75, v43, v7
	v_fmac_f32_e32 v72, v44, v7
	v_fmac_f32_e32 v73, v45, v7
	ds_read_b128 v[28:31], v6 offset:1472
	ds_read_b128 v[32:35], v6 offset:1488
	ds_read_b32 v36, v47 offset:184
	ds_read_b128 v[38:41], v6 offset:1504
	ds_read_b128 v[42:45], v6 offset:1520
	ds_read_b32 v46, v47 offset:188
	s_waitcnt lgkmcnt(0)
	v_mul_f32_e32 v7, v160, v36
	v_fmac_f32_e32 v68, v28, v7
	v_fmac_f32_e32 v69, v29, v7
	v_fmac_f32_e32 v70, v30, v7
	v_fmac_f32_e32 v71, v31, v7
	v_fmac_f32_e32 v74, v32, v7
	v_fmac_f32_e32 v75, v33, v7
	v_fmac_f32_e32 v72, v34, v7
	v_fmac_f32_e32 v73, v35, v7
	v_mul_f32_e32 v7, v161, v46
	v_fmac_f32_e32 v68, v38, v7
	v_fmac_f32_e32 v69, v39, v7
	v_fmac_f32_e32 v70, v40, v7
	v_fmac_f32_e32 v71, v41, v7
	v_fmac_f32_e32 v74, v42, v7
	v_fmac_f32_e32 v75, v43, v7
	v_fmac_f32_e32 v72, v44, v7
	v_fmac_f32_e32 v73, v45, v7
	ds_read_b128 v[28:31], v6 offset:1536
	ds_read_b128 v[32:35], v6 offset:1552
	ds_read_b32 v36, v47 offset:192
	ds_read_b128 v[38:41], v6 offset:1568
	ds_read_b128 v[42:45], v6 offset:1584
	ds_read_b32 v46, v47 offset:196
	s_waitcnt lgkmcnt(0)
	v_mul_f32_e32 v7, v162, v36
	v_fmac_f32_e32 v68, v28, v7
	v_fmac_f32_e32 v69, v29, v7
	v_fmac_f32_e32 v70, v30, v7
	v_fmac_f32_e32 v71, v31, v7
	v_fmac_f32_e32 v74, v32, v7
	v_fmac_f32_e32 v75, v33, v7
	v_fmac_f32_e32 v72, v34, v7
	v_fmac_f32_e32 v73, v35, v7
	v_mul_f32_e32 v7, v163, v46
	v_fmac_f32_e32 v68, v38, v7
	v_fmac_f32_e32 v69, v39, v7
	v_fmac_f32_e32 v70, v40, v7
	v_fmac_f32_e32 v71, v41, v7
	v_fmac_f32_e32 v74, v42, v7
	v_fmac_f32_e32 v75, v43, v7
	v_fmac_f32_e32 v72, v44, v7
	v_fmac_f32_e32 v73, v45, v7
	ds_read_b128 v[28:31], v6 offset:1600
	ds_read_b128 v[32:35], v6 offset:1616
	ds_read_b32 v36, v47 offset:200
	ds_read_b128 v[38:41], v6 offset:1632
	ds_read_b128 v[42:45], v6 offset:1648
	ds_read_b32 v46, v47 offset:204
	s_waitcnt lgkmcnt(0)
; __device__ __forceinline__ unsigned f2bf(float f) { unsigned u = __builtin_bit_cast(unsigned, f); return (u + 0x7fffu + ((u >> 16) & 1u)) >> 16; }
; __device__ __forceinline__ void weights_phase(int l, LAS unsigned char* lds, int vcu, int G, int wave, int lane) {
;     ...
;             for (int e = 0; e < 128; ++e) { const float cf = wp[e] * ps[e]; a0 += cf * *(const f32x4*)(wb + (size_t)e * 1024); a1 += cf * *(const f32x4*)(wb + (size_t)e * 1024 + 4); }
;             bf16* dst = WBR + (size_t)(1024 + cblk * 8) * 512 + g * 128 + ci;
;             dst[0 * 512] = (bf16)f2bf(a0.x); dst[1 * 512] = (bf16)f2bf(a0.y); dst[2 * 512] = (bf16)f2bf(a0.z); dst[3 * 512] = (bf16)f2bf(a0.w);
;             dst[4 * 512] = (bf16)f2bf(a1.x); dst[5 * 512] = (bf16)f2bf(a1.y); dst[6 * 512] = (bf16)f2bf(a1.z); dst[7 * 512] = (bf16)f2bf(a1.w);
	v_mul_f32_e32 v7, v164, v36
	v_fmac_f32_e32 v68, v28, v7
	v_fmac_f32_e32 v69, v29, v7
	v_fmac_f32_e32 v70, v30, v7
	v_fmac_f32_e32 v71, v31, v7
	v_fmac_f32_e32 v74, v32, v7
	v_fmac_f32_e32 v75, v33, v7
	v_fmac_f32_e32 v72, v34, v7
	v_fmac_f32_e32 v73, v35, v7
	v_mul_f32_e32 v7, v165, v46
	v_fmac_f32_e32 v68, v38, v7
	v_fmac_f32_e32 v69, v39, v7
	v_fmac_f32_e32 v70, v40, v7
	v_fmac_f32_e32 v71, v41, v7
	v_fmac_f32_e32 v74, v42, v7
	v_fmac_f32_e32 v75, v43, v7
	v_fmac_f32_e32 v72, v44, v7
	v_fmac_f32_e32 v73, v45, v7
	ds_read_b128 v[28:31], v6 offset:1664
	ds_read_b128 v[32:35], v6 offset:1680
	ds_read_b32 v36, v47 offset:208
	ds_read_b128 v[38:41], v6 offset:1696
	ds_read_b128 v[42:45], v6 offset:1712
	ds_read_b32 v46, v47 offset:212
	s_waitcnt lgkmcnt(0)
	v_mul_f32_e32 v7, v166, v36
	v_fmac_f32_e32 v68, v28, v7
	v_fmac_f32_e32 v69, v29, v7
	v_fmac_f32_e32 v70, v30, v7
	v_fmac_f32_e32 v71, v31, v7
	v_fmac_f32_e32 v74, v32, v7
	v_fmac_f32_e32 v75, v33, v7
	v_fmac_f32_e32 v72, v34, v7
	v_fmac_f32_e32 v73, v35, v7
	v_mul_f32_e32 v7, v167, v46
	v_fmac_f32_e32 v68, v38, v7
	v_fmac_f32_e32 v69, v39, v7
	v_fmac_f32_e32 v70, v40, v7
	v_fmac_f32_e32 v71, v41, v7
	v_fmac_f32_e32 v74, v42, v7
	v_fmac_f32_e32 v75, v43, v7
	v_fmac_f32_e32 v72, v44, v7
	v_fmac_f32_e32 v73, v45, v7
	ds_read_b128 v[28:31], v6 offset:1728
	ds_read_b128 v[32:35], v6 offset:1744
	ds_read_b32 v36, v47 offset:216
	ds_read_b128 v[38:41], v6 offset:1760
	ds_read_b128 v[42:45], v6 offset:1776
	ds_read_b32 v46, v47 offset:220
	s_waitcnt lgkmcnt(0)
	v_mul_f32_e32 v7, v168, v36
	v_fmac_f32_e32 v68, v28, v7
	v_fmac_f32_e32 v69, v29, v7
	v_fmac_f32_e32 v70, v30, v7
	v_fmac_f32_e32 v71, v31, v7
	v_fmac_f32_e32 v74, v32, v7
	v_fmac_f32_e32 v75, v33, v7
	v_fmac_f32_e32 v72, v34, v7
	v_fmac_f32_e32 v73, v35, v7
	v_mul_f32_e32 v7, v169, v46
	v_fmac_f32_e32 v68, v38, v7
	v_fmac_f32_e32 v69, v39, v7
	v_fmac_f32_e32 v70, v40, v7
	v_fmac_f32_e32 v71, v41, v7
	v_fmac_f32_e32 v74, v42, v7
	v_fmac_f32_e32 v75, v43, v7
	v_fmac_f32_e32 v72, v44, v7
	v_fmac_f32_e32 v73, v45, v7
	ds_read_b128 v[28:31], v6 offset:1792
	ds_read_b128 v[32:35], v6 offset:1808
	ds_read_b32 v36, v47 offset:224
	ds_read_b128 v[38:41], v6 offset:1824
	ds_read_b128 v[42:45], v6 offset:1840
	ds_read_b32 v46, v47 offset:228
	s_waitcnt lgkmcnt(0)
	v_mul_f32_e32 v7, v170, v36
	v_fmac_f32_e32 v68, v28, v7
	v_fmac_f32_e32 v69, v29, v7
	v_fmac_f32_e32 v70, v30, v7
	v_fmac_f32_e32 v71, v31, v7
	v_fmac_f32_e32 v74, v32, v7
	v_fmac_f32_e32 v75, v33, v7
	v_fmac_f32_e32 v72, v34, v7
	v_fmac_f32_e32 v73, v35, v7
	v_mul_f32_e32 v7, v171, v46
	v_fmac_f32_e32 v68, v38, v7
	v_fmac_f32_e32 v69, v39, v7
	v_fmac_f32_e32 v70, v40, v7
	v_fmac_f32_e32 v71, v41, v7
	v_fmac_f32_e32 v74, v42, v7
	v_fmac_f32_e32 v75, v43, v7
	v_fmac_f32_e32 v72, v44, v7
	v_fmac_f32_e32 v73, v45, v7
	ds_read_b128 v[28:31], v6 offset:1856
	ds_read_b128 v[32:35], v6 offset:1872
	ds_read_b32 v36, v47 offset:232
	ds_read_b128 v[38:41], v6 offset:1888
	ds_read_b128 v[42:45], v6 offset:1904
	ds_read_b32 v46, v47 offset:236
	s_waitcnt lgkmcnt(0)
	v_mul_f32_e32 v7, v172, v36
	v_fmac_f32_e32 v68, v28, v7
	v_fmac_f32_e32 v69, v29, v7
	v_fmac_f32_e32 v70, v30, v7
	v_fmac_f32_e32 v71, v31, v7
	v_fmac_f32_e32 v74, v32, v7
	v_fmac_f32_e32 v75, v33, v7
	v_fmac_f32_e32 v72, v34, v7
	v_fmac_f32_e32 v73, v35, v7
	v_mul_f32_e32 v7, v173, v46
	v_fmac_f32_e32 v68, v38, v7
	v_fmac_f32_e32 v69, v39, v7
	v_fmac_f32_e32 v70, v40, v7
	v_fmac_f32_e32 v71, v41, v7
	v_fmac_f32_e32 v74, v42, v7
	v_fmac_f32_e32 v75, v43, v7
	v_fmac_f32_e32 v72, v44, v7
	v_fmac_f32_e32 v73, v45, v7
	ds_read_b128 v[28:31], v6 offset:1920
	ds_read_b128 v[32:35], v6 offset:1936
	ds_read_b32 v36, v47 offset:240
	ds_read_b128 v[38:41], v6 offset:1952
	ds_read_b128 v[42:45], v6 offset:1968
	ds_read_b32 v46, v47 offset:244
	s_waitcnt lgkmcnt(0)
	v_mul_f32_e32 v7, v174, v36
	v_fmac_f32_e32 v68, v28, v7
	v_fmac_f32_e32 v69, v29, v7
	v_fmac_f32_e32 v70, v30, v7
	v_fmac_f32_e32 v71, v31, v7
	v_fmac_f32_e32 v74, v32, v7
	v_fmac_f32_e32 v75, v33, v7
	v_fmac_f32_e32 v72, v34, v7
	v_fmac_f32_e32 v73, v35, v7
	v_mul_f32_e32 v7, v175, v46
	v_fmac_f32_e32 v68, v38, v7
	v_fmac_f32_e32 v69, v39, v7
	v_fmac_f32_e32 v70, v40, v7
	v_fmac_f32_e32 v71, v41, v7
	v_fmac_f32_e32 v74, v42, v7
	v_fmac_f32_e32 v75, v43, v7
	v_fmac_f32_e32 v72, v44, v7
	v_fmac_f32_e32 v73, v45, v7
	ds_read_b128 v[28:31], v6 offset:1984
	ds_read_b128 v[32:35], v6 offset:2000
	ds_read_b32 v36, v47 offset:248
	ds_read_b128 v[38:41], v6 offset:2016
	ds_read_b128 v[42:45], v6 offset:2032
	ds_read_b32 v46, v47 offset:252
	s_waitcnt lgkmcnt(0)
	v_mul_f32_e32 v7, v176, v36
	v_fmac_f32_e32 v68, v28, v7
	v_fmac_f32_e32 v69, v29, v7
	v_fmac_f32_e32 v70, v30, v7
	v_fmac_f32_e32 v71, v31, v7
	v_fmac_f32_e32 v74, v32, v7
	v_fmac_f32_e32 v75, v33, v7
	v_fmac_f32_e32 v72, v34, v7
	v_fmac_f32_e32 v73, v35, v7
	v_mul_f32_e32 v7, v177, v46
	v_fmac_f32_e32 v68, v38, v7
	v_fmac_f32_e32 v69, v39, v7
	v_fmac_f32_e32 v70, v40, v7
	v_fmac_f32_e32 v71, v41, v7
	v_fmac_f32_e32 v74, v42, v7
	v_fmac_f32_e32 v75, v43, v7
	v_fmac_f32_e32 v72, v44, v7
	v_fmac_f32_e32 v73, v45, v7
	v_add_u32_e32 v6, 0x800, v6
	v_add_u32_e32 v47, 0x100, v47
	v_add_co_u32_e32 v8, vcc, 0x100, v8
	s_nop 1
	v_addc_co_u32_e32 v9, vcc, 0, v9, vcc
	s_add_u32 s21, s21, 1
	s_cmp_lt_u32 s21, 2
	s_cbranch_scc1 .Lweff_half_a
	s_lshr_b32 s0, s3, 1
	v_and_or_b32 v0, s0, 64, v59
	s_lshl_b32 s0, s3, 13
	s_and_b32 s0, s0, 0xfe000
	s_add_u32 s6, s4, s0
	s_addc_u32 s14, s5, 0
	s_lshl_b64 s[0:1], s[12:13], 1
	s_add_u32 s0, s6, s0
	s_addc_u32 s1, s14, s1
	v_lshlrev_b32_e32 v0, 1, v0
	v_mov_b32_e32 v1, v57
	v_lshl_add_u64 v[0:1], s[0:1], 0, v[0:1]
	v_lshl_add_u64 v[2:3], v[0:1], 0, s[10:11]
	v_bfe_u32 v4, v68, 16, 1
	v_add_co_u32_e32 v0, vcc, s53, v0
	v_add3_u32 v4, v68, v4, s37
	s_nop 0
	v_addc_co_u32_e32 v1, vcc, 0, v1, vcc
	global_store_short_d16_hi v[0:1], v4, off offset:-4096
	v_bfe_u32 v4, v69, 16, 1
	v_add3_u32 v4, v69, v4, s37
	global_store_short_d16_hi v[2:3], v4, off offset:1024
	v_bfe_u32 v4, v70, 16, 1
	v_add3_u32 v4, v70, v4, s37
	global_store_short_d16_hi v[2:3], v4, off offset:2048
	v_bfe_u32 v4, v71, 16, 1
	v_add3_u32 v4, v71, v4, s37
	global_store_short_d16_hi v[2:3], v4, off offset:3072
	v_bfe_u32 v2, v74, 16, 1
	v_add3_u32 v2, v74, v2, s37
	global_store_short_d16_hi v[0:1], v2, off
	v_bfe_u32 v2, v75, 16, 1
	v_add3_u32 v2, v75, v2, s37
	global_store_short_d16_hi v[0:1], v2, off offset:1024
	v_bfe_u32 v2, v72, 16, 1
	v_add3_u32 v2, v72, v2, s37
	global_store_short_d16_hi v[0:1], v2, off offset:2048
	v_bfe_u32 v2, v73, 16, 1
	v_add3_u32 v2, v73, v2, s37
	global_store_short_d16_hi v[0:1], v2, off offset:3072
	s_branch .LBB0_96

; #define ARG_IN(i) argp(i)
; __device__ __forceinline__ void weights_phase(int l, LAS unsigned char* lds, int vcu, int G, int wave, int lane) {
;     ...
;             const int cblk = r & 127, kh = (r >> 7) & 1, g = r >> 8, ci = kh * 64 + lane;
;             const float* wp = ARG_IN(12) + ((size_t)(l * 4 + g) * 128 + ci) * 128; const float* ps = ARG_IN(13) + l * 512 + g * 128;
;             const float* wb = ARG_IN(14) + ((size_t)(l * 3 + 1) * 512 + g * 128) * 1024 + cblk * 8;
;             f32x4 a0 = {0.f, 0.f, 0.f, 0.f}, a1 = {0.f, 0.f, 0.f, 0.f};
; #pragma unroll 16
;             for (int e = 0; e < 128; ++e) { const float cf = wp[e] * ps[e]; a0 += cf * *(const f32x4*)(wb + (size_t)e * 1024); a1 += cf * *(const f32x4*)(wb + (size_t)e * 1024 + 4); }
.LBB0_213:
	v_mbcnt_lo_u32_b32 v0, -1, 0
	v_mbcnt_hi_u32_b32 v0, -1, v0
	v_readlane_b32 s16, v255, 4
	v_lshrrev_b32_e32 v4, 1, v0
	v_lshlrev_b32_e32 v4, 12, v4
	v_and_b32_e32 v3, 1, v0
	v_lshl_or_b32 v3, v3, 4, v4
	s_lshl_b32 s16, s16, 14
	v_lshlrev_b32_e32 v5, 3, v0
	s_add_u32 s28, s25, 0x800000
	s_addc_u32 s29, s26, 0
	global_load_dwordx4 v[82:85], v3, s[28:29]
	s_add_u32 s28, s28, 0x20000
	s_addc_u32 s29, s29, 0
	global_load_dwordx4 v[86:89], v3, s[28:29]
	s_add_u32 s28, s28, 0x20000
	s_addc_u32 s29, s29, 0
	global_load_dwordx4 v[90:93], v3, s[28:29]
	s_add_u32 s28, s28, 0x20000
	s_addc_u32 s29, s29, 0
	global_load_dwordx4 v[94:97], v3, s[28:29]
	global_load_dwordx2 v[98:99], v5, s[0:1] offset:2048
	v_lshl_add_u32 v2, v0, 4, s16
	v_lshl_add_u32 v6, v0, 3, s16
	v_mov_b32_e32 v7, s16
	v_add_u32_e32 v9, 0x1000, v7
	v_lshl_add_u64 v[10:11], v[36:37], 0, s[46:47]
	s_waitcnt vmcnt(0)
	ds_write_b128 v2, v[82:85]
	ds_write_b128 v2, v[86:89] offset:1024
	ds_write_b128 v2, v[90:93] offset:2048
	ds_write_b128 v2, v[94:97] offset:3072
	ds_write_b64 v6, v[98:99] offset:4096
	s_mov_b32 s17, 0
	s_waitcnt lgkmcnt(0)
.Lweff_half_b:
	global_load_dwordx4 v[100:103], v[10:11], off
	global_load_dwordx4 v[104:107], v[10:11], off offset:16
	global_load_dwordx4 v[108:111], v[10:11], off offset:32
	global_load_dwordx4 v[112:115], v[10:11], off offset:48
	global_load_dwordx4 v[116:119], v[10:11], off offset:64
	global_load_dwordx4 v[120:123], v[10:11], off offset:80
	global_load_dwordx4 v[124:127], v[10:11], off offset:96
	global_load_dwordx4 v[128:131], v[10:11], off offset:112
	global_load_dwordx4 v[132:135], v[10:11], off offset:128
	global_load_dwordx4 v[136:139], v[10:11], off offset:144
	global_load_dwordx4 v[140:143], v[10:11], off offset:160
	global_load_dwordx4 v[144:147], v[10:11], off offset:176
	global_load_dwordx4 v[148:151], v[10:11], off offset:192
	global_load_dwordx4 v[152:155], v[10:11], off offset:208
	global_load_dwordx4 v[156:159], v[10:11], off offset:224
	global_load_dwordx4 v[160:163], v[10:11], off offset:240
	s_waitcnt vmcnt(0)
	ds_read_b128 v[66:69], v7
	ds_read_b128 v[70:73], v7 offset:16
	ds_read_b32 v74, v9
	ds_read_b128 v[12:15], v7 offset:32
	ds_read_b128 v[16:19], v7 offset:48
	ds_read_b32 v20, v9 offset:4
	s_waitcnt lgkmcnt(0)
	v_mul_f32_e32 v8, v100, v74
	v_fmac_f32_e32 v42, v66, v8
	v_fmac_f32_e32 v43, v67, v8
	v_fmac_f32_e32 v44, v68, v8
	v_fmac_f32_e32 v45, v69, v8
	v_fmac_f32_e32 v40, v70, v8
	v_fmac_f32_e32 v41, v71, v8
	v_fmac_f32_e32 v38, v72, v8
	v_fmac_f32_e32 v39, v73, v8
	v_mul_f32_e32 v8, v101, v20
	v_fmac_f32_e32 v42, v12, v8
	v_fmac_f32_e32 v43, v13, v8
	v_fmac_f32_e32 v44, v14, v8
	v_fmac_f32_e32 v45, v15, v8
	v_fmac_f32_e32 v40, v16, v8
	v_fmac_f32_e32 v41, v17, v8
	v_fmac_f32_e32 v38, v18, v8
	v_fmac_f32_e32 v39, v19, v8
	ds_read_b128 v[66:69], v7 offset:64
	ds_read_b128 v[70:73], v7 offset:80
	ds_read_b32 v74, v9 offset:8
	ds_read_b128 v[12:15], v7 offset:96
	ds_read_b128 v[16:19], v7 offset:112
	ds_read_b32 v20, v9 offset:12
	s_waitcnt lgkmcnt(0)
	v_mul_f32_e32 v8, v102, v74
	v_fmac_f32_e32 v42, v66, v8
	v_fmac_f32_e32 v43, v67, v8
	v_fmac_f32_e32 v44, v68, v8
	v_fmac_f32_e32 v45, v69, v8
	v_fmac_f32_e32 v40, v70, v8
	v_fmac_f32_e32 v41, v71, v8
	v_fmac_f32_e32 v38, v72, v8
	v_fmac_f32_e32 v39, v73, v8
	v_mul_f32_e32 v8, v103, v20
	v_fmac_f32_e32 v42, v12, v8
	v_fmac_f32_e32 v43, v13, v8
	v_fmac_f32_e32 v44, v14, v8
	v_fmac_f32_e32 v45, v15, v8
	v_fmac_f32_e32 v40, v16, v8
	v_fmac_f32_e32 v41, v17, v8
	v_fmac_f32_e32 v38, v18, v8
	v_fmac_f32_e32 v39, v19, v8
	ds_read_b128 v[66:69], v7 offset:128
	ds_read_b128 v[70:73], v7 offset:144
	ds_read_b32 v74, v9 offset:16
	ds_read_b128 v[12:15], v7 offset:160
	ds_read_b128 v[16:19], v7 offset:176
	ds_read_b32 v20, v9 offset:20
	s_waitcnt lgkmcnt(0)
	v_mul_f32_e32 v8, v104, v74
	v_fmac_f32_e32 v42, v66, v8
	v_fmac_f32_e32 v43, v67, v8
	v_fmac_f32_e32 v44, v68, v8
	v_fmac_f32_e32 v45, v69, v8
	v_fmac_f32_e32 v40, v70, v8
	v_fmac_f32_e32 v41, v71, v8
	v_fmac_f32_e32 v38, v72, v8
	v_fmac_f32_e32 v39, v73, v8
	v_mul_f32_e32 v8, v105, v20
	v_fmac_f32_e32 v42, v12, v8
	v_fmac_f32_e32 v43, v13, v8
	v_fmac_f32_e32 v44, v14, v8
	v_fmac_f32_e32 v45, v15, v8
	v_fmac_f32_e32 v40, v16, v8
	v_fmac_f32_e32 v41, v17, v8
	v_fmac_f32_e32 v38, v18, v8
	v_fmac_f32_e32 v39, v19, v8
	ds_read_b128 v[66:69], v7 offset:192
	ds_read_b128 v[70:73], v7 offset:208
	ds_read_b32 v74, v9 offset:24
	ds_read_b128 v[12:15], v7 offset:224
	ds_read_b128 v[16:19], v7 offset:240
	ds_read_b32 v20, v9 offset:28
	s_waitcnt lgkmcnt(0)
	v_mul_f32_e32 v8, v106, v74
	v_fmac_f32_e32 v42, v66, v8
	v_fmac_f32_e32 v43, v67, v8
	v_fmac_f32_e32 v44, v68, v8
	v_fmac_f32_e32 v45, v69, v8
	v_fmac_f32_e32 v40, v70, v8
	v_fmac_f32_e32 v41, v71, v8
	v_fmac_f32_e32 v38, v72, v8
	v_fmac_f32_e32 v39, v73, v8
	v_mul_f32_e32 v8, v107, v20
	v_fmac_f32_e32 v42, v12, v8
	v_fmac_f32_e32 v43, v13, v8
	v_fmac_f32_e32 v44, v14, v8
	v_fmac_f32_e32 v45, v15, v8
	v_fmac_f32_e32 v40, v16, v8
	v_fmac_f32_e32 v41, v17, v8
	v_fmac_f32_e32 v38, v18, v8
	v_fmac_f32_e32 v39, v19, v8
	ds_read_b128 v[66:69], v7 offset:256
	ds_read_b128 v[70:73], v7 offset:272
	ds_read_b32 v74, v9 offset:32
	ds_read_b128 v[12:15], v7 offset:288
	ds_read_b128 v[16:19], v7 offset:304
	ds_read_b32 v20, v9 offset:36
	s_waitcnt lgkmcnt(0)
; __device__ __forceinline__ void weights_phase(int l, LAS unsigned char* lds, int vcu, int G, int wave, int lane) {
;     ...
; #pragma unroll 16
;             for (int e = 0; e < 128; ++e) { const float cf = wp[e] * ps[e]; a0 += cf * *(const f32x4*)(wb + (size_t)e * 1024); a1 += cf * *(const f32x4*)(wb + (size_t)e * 1024 + 4); }
	v_mul_f32_e32 v8, v108, v74
	v_fmac_f32_e32 v42, v66, v8
	v_fmac_f32_e32 v43, v67, v8
	v_fmac_f32_e32 v44, v68, v8
	v_fmac_f32_e32 v45, v69, v8
	v_fmac_f32_e32 v40, v70, v8
	v_fmac_f32_e32 v41, v71, v8
	v_fmac_f32_e32 v38, v72, v8
	v_fmac_f32_e32 v39, v73, v8
	v_mul_f32_e32 v8, v109, v20
	v_fmac_f32_e32 v42, v12, v8
	v_fmac_f32_e32 v43, v13, v8
	v_fmac_f32_e32 v44, v14, v8
	v_fmac_f32_e32 v45, v15, v8
	v_fmac_f32_e32 v40, v16, v8
	v_fmac_f32_e32 v41, v17, v8
	v_fmac_f32_e32 v38, v18, v8
	v_fmac_f32_e32 v39, v19, v8
	ds_read_b128 v[66:69], v7 offset:320
	ds_read_b128 v[70:73], v7 offset:336
	ds_read_b32 v74, v9 offset:40
	ds_read_b128 v[12:15], v7 offset:352
	ds_read_b128 v[16:19], v7 offset:368
	ds_read_b32 v20, v9 offset:44
	s_waitcnt lgkmcnt(0)
	v_mul_f32_e32 v8, v110, v74
	v_fmac_f32_e32 v42, v66, v8
	v_fmac_f32_e32 v43, v67, v8
	v_fmac_f32_e32 v44, v68, v8
	v_fmac_f32_e32 v45, v69, v8
	v_fmac_f32_e32 v40, v70, v8
	v_fmac_f32_e32 v41, v71, v8
	v_fmac_f32_e32 v38, v72, v8
	v_fmac_f32_e32 v39, v73, v8
	v_mul_f32_e32 v8, v111, v20
	v_fmac_f32_e32 v42, v12, v8
	v_fmac_f32_e32 v43, v13, v8
	v_fmac_f32_e32 v44, v14, v8
	v_fmac_f32_e32 v45, v15, v8
	v_fmac_f32_e32 v40, v16, v8
	v_fmac_f32_e32 v41, v17, v8
	v_fmac_f32_e32 v38, v18, v8
	v_fmac_f32_e32 v39, v19, v8
	ds_read_b128 v[66:69], v7 offset:384
	ds_read_b128 v[70:73], v7 offset:400
	ds_read_b32 v74, v9 offset:48
	ds_read_b128 v[12:15], v7 offset:416
	ds_read_b128 v[16:19], v7 offset:432
	ds_read_b32 v20, v9 offset:52
	s_waitcnt lgkmcnt(0)
	v_mul_f32_e32 v8, v112, v74
	v_fmac_f32_e32 v42, v66, v8
	v_fmac_f32_e32 v43, v67, v8
	v_fmac_f32_e32 v44, v68, v8
	v_fmac_f32_e32 v45, v69, v8
	v_fmac_f32_e32 v40, v70, v8
	v_fmac_f32_e32 v41, v71, v8
	v_fmac_f32_e32 v38, v72, v8
	v_fmac_f32_e32 v39, v73, v8
	v_mul_f32_e32 v8, v113, v20
	v_fmac_f32_e32 v42, v12, v8
	v_fmac_f32_e32 v43, v13, v8
	v_fmac_f32_e32 v44, v14, v8
	v_fmac_f32_e32 v45, v15, v8
	v_fmac_f32_e32 v40, v16, v8
	v_fmac_f32_e32 v41, v17, v8
	v_fmac_f32_e32 v38, v18, v8
	v_fmac_f32_e32 v39, v19, v8
	ds_read_b128 v[66:69], v7 offset:448
	ds_read_b128 v[70:73], v7 offset:464
	ds_read_b32 v74, v9 offset:56
	ds_read_b128 v[12:15], v7 offset:480
	ds_read_b128 v[16:19], v7 offset:496
	ds_read_b32 v20, v9 offset:60
	s_waitcnt lgkmcnt(0)
	v_mul_f32_e32 v8, v114, v74
	v_fmac_f32_e32 v42, v66, v8
	v_fmac_f32_e32 v43, v67, v8
	v_fmac_f32_e32 v44, v68, v8
	v_fmac_f32_e32 v45, v69, v8
	v_fmac_f32_e32 v40, v70, v8
	v_fmac_f32_e32 v41, v71, v8
	v_fmac_f32_e32 v38, v72, v8
	v_fmac_f32_e32 v39, v73, v8
	v_mul_f32_e32 v8, v115, v20
	v_fmac_f32_e32 v42, v12, v8
	v_fmac_f32_e32 v43, v13, v8
	v_fmac_f32_e32 v44, v14, v8
	v_fmac_f32_e32 v45, v15, v8
	v_fmac_f32_e32 v40, v16, v8
	v_fmac_f32_e32 v41, v17, v8
	v_fmac_f32_e32 v38, v18, v8
	v_fmac_f32_e32 v39, v19, v8
	ds_read_b128 v[66:69], v7 offset:512
	ds_read_b128 v[70:73], v7 offset:528
	ds_read_b32 v74, v9 offset:64
	ds_read_b128 v[12:15], v7 offset:544
	ds_read_b128 v[16:19], v7 offset:560
	ds_read_b32 v20, v9 offset:68
	s_waitcnt lgkmcnt(0)
	v_mul_f32_e32 v8, v116, v74
	v_fmac_f32_e32 v42, v66, v8
	v_fmac_f32_e32 v43, v67, v8
	v_fmac_f32_e32 v44, v68, v8
	v_fmac_f32_e32 v45, v69, v8
	v_fmac_f32_e32 v40, v70, v8
	v_fmac_f32_e32 v41, v71, v8
	v_fmac_f32_e32 v38, v72, v8
	v_fmac_f32_e32 v39, v73, v8
	v_mul_f32_e32 v8, v117, v20
	v_fmac_f32_e32 v42, v12, v8
	v_fmac_f32_e32 v43, v13, v8
	v_fmac_f32_e32 v44, v14, v8
	v_fmac_f32_e32 v45, v15, v8
	v_fmac_f32_e32 v40, v16, v8
	v_fmac_f32_e32 v41, v17, v8
	v_fmac_f32_e32 v38, v18, v8
	v_fmac_f32_e32 v39, v19, v8
	ds_read_b128 v[66:69], v7 offset:576
	ds_read_b128 v[70:73], v7 offset:592
	ds_read_b32 v74, v9 offset:72
	ds_read_b128 v[12:15], v7 offset:608
	ds_read_b128 v[16:19], v7 offset:624
	ds_read_b32 v20, v9 offset:76
	s_waitcnt lgkmcnt(0)
	v_mul_f32_e32 v8, v118, v74
	v_fmac_f32_e32 v42, v66, v8
	v_fmac_f32_e32 v43, v67, v8
	v_fmac_f32_e32 v44, v68, v8
	v_fmac_f32_e32 v45, v69, v8
	v_fmac_f32_e32 v40, v70, v8
	v_fmac_f32_e32 v41, v71, v8
	v_fmac_f32_e32 v38, v72, v8
	v_fmac_f32_e32 v39, v73, v8
	v_mul_f32_e32 v8, v119, v20
	v_fmac_f32_e32 v42, v12, v8
	v_fmac_f32_e32 v43, v13, v8
	v_fmac_f32_e32 v44, v14, v8
	v_fmac_f32_e32 v45, v15, v8
	v_fmac_f32_e32 v40, v16, v8
	v_fmac_f32_e32 v41, v17, v8
	v_fmac_f32_e32 v38, v18, v8
	v_fmac_f32_e32 v39, v19, v8
	ds_read_b128 v[66:69], v7 offset:640
	ds_read_b128 v[70:73], v7 offset:656
	ds_read_b32 v74, v9 offset:80
	ds_read_b128 v[12:15], v7 offset:672
	ds_read_b128 v[16:19], v7 offset:688
	ds_read_b32 v20, v9 offset:84
	s_waitcnt lgkmcnt(0)
	v_mul_f32_e32 v8, v120, v74
	v_fmac_f32_e32 v42, v66, v8
	v_fmac_f32_e32 v43, v67, v8
	v_fmac_f32_e32 v44, v68, v8
	v_fmac_f32_e32 v45, v69, v8
	v_fmac_f32_e32 v40, v70, v8
	v_fmac_f32_e32 v41, v71, v8
	v_fmac_f32_e32 v38, v72, v8
	v_fmac_f32_e32 v39, v73, v8
	v_mul_f32_e32 v8, v121, v20
	v_fmac_f32_e32 v42, v12, v8
	v_fmac_f32_e32 v43, v13, v8
	v_fmac_f32_e32 v44, v14, v8
	v_fmac_f32_e32 v45, v15, v8
	v_fmac_f32_e32 v40, v16, v8
	v_fmac_f32_e32 v41, v17, v8
	v_fmac_f32_e32 v38, v18, v8
	v_fmac_f32_e32 v39, v19, v8
	ds_read_b128 v[66:69], v7 offset:704
	ds_read_b128 v[70:73], v7 offset:720
	ds_read_b32 v74, v9 offset:88
	ds_read_b128 v[12:15], v7 offset:736
	ds_read_b128 v[16:19], v7 offset:752
	ds_read_b32 v20, v9 offset:92
	s_waitcnt lgkmcnt(0)
; __device__ __forceinline__ void weights_phase(int l, LAS unsigned char* lds, int vcu, int G, int wave, int lane) {
;     ...
; #pragma unroll 16
;             for (int e = 0; e < 128; ++e) { const float cf = wp[e] * ps[e]; a0 += cf * *(const f32x4*)(wb + (size_t)e * 1024); a1 += cf * *(const f32x4*)(wb + (size_t)e * 1024 + 4); }
	v_mul_f32_e32 v8, v122, v74
	v_fmac_f32_e32 v42, v66, v8
	v_fmac_f32_e32 v43, v67, v8
	v_fmac_f32_e32 v44, v68, v8
	v_fmac_f32_e32 v45, v69, v8
	v_fmac_f32_e32 v40, v70, v8
	v_fmac_f32_e32 v41, v71, v8
	v_fmac_f32_e32 v38, v72, v8
	v_fmac_f32_e32 v39, v73, v8
	v_mul_f32_e32 v8, v123, v20
	v_fmac_f32_e32 v42, v12, v8
	v_fmac_f32_e32 v43, v13, v8
	v_fmac_f32_e32 v44, v14, v8
	v_fmac_f32_e32 v45, v15, v8
	v_fmac_f32_e32 v40, v16, v8
	v_fmac_f32_e32 v41, v17, v8
	v_fmac_f32_e32 v38, v18, v8
	v_fmac_f32_e32 v39, v19, v8
	ds_read_b128 v[66:69], v7 offset:768
	ds_read_b128 v[70:73], v7 offset:784
	ds_read_b32 v74, v9 offset:96
	ds_read_b128 v[12:15], v7 offset:800
	ds_read_b128 v[16:19], v7 offset:816
	ds_read_b32 v20, v9 offset:100
	s_waitcnt lgkmcnt(0)
	v_mul_f32_e32 v8, v124, v74
	v_fmac_f32_e32 v42, v66, v8
	v_fmac_f32_e32 v43, v67, v8
	v_fmac_f32_e32 v44, v68, v8
	v_fmac_f32_e32 v45, v69, v8
	v_fmac_f32_e32 v40, v70, v8
	v_fmac_f32_e32 v41, v71, v8
	v_fmac_f32_e32 v38, v72, v8
	v_fmac_f32_e32 v39, v73, v8
	v_mul_f32_e32 v8, v125, v20
	v_fmac_f32_e32 v42, v12, v8
	v_fmac_f32_e32 v43, v13, v8
	v_fmac_f32_e32 v44, v14, v8
	v_fmac_f32_e32 v45, v15, v8
	v_fmac_f32_e32 v40, v16, v8
	v_fmac_f32_e32 v41, v17, v8
	v_fmac_f32_e32 v38, v18, v8
	v_fmac_f32_e32 v39, v19, v8
	ds_read_b128 v[66:69], v7 offset:832
	ds_read_b128 v[70:73], v7 offset:848
	ds_read_b32 v74, v9 offset:104
	ds_read_b128 v[12:15], v7 offset:864
	ds_read_b128 v[16:19], v7 offset:880
	ds_read_b32 v20, v9 offset:108
	s_waitcnt lgkmcnt(0)
	v_mul_f32_e32 v8, v126, v74
	v_fmac_f32_e32 v42, v66, v8
	v_fmac_f32_e32 v43, v67, v8
	v_fmac_f32_e32 v44, v68, v8
	v_fmac_f32_e32 v45, v69, v8
	v_fmac_f32_e32 v40, v70, v8
	v_fmac_f32_e32 v41, v71, v8
	v_fmac_f32_e32 v38, v72, v8
	v_fmac_f32_e32 v39, v73, v8
	v_mul_f32_e32 v8, v127, v20
	v_fmac_f32_e32 v42, v12, v8
	v_fmac_f32_e32 v43, v13, v8
	v_fmac_f32_e32 v44, v14, v8
	v_fmac_f32_e32 v45, v15, v8
	v_fmac_f32_e32 v40, v16, v8
	v_fmac_f32_e32 v41, v17, v8
	v_fmac_f32_e32 v38, v18, v8
	v_fmac_f32_e32 v39, v19, v8
	ds_read_b128 v[66:69], v7 offset:896
	ds_read_b128 v[70:73], v7 offset:912
	ds_read_b32 v74, v9 offset:112
	ds_read_b128 v[12:15], v7 offset:928
	ds_read_b128 v[16:19], v7 offset:944
	ds_read_b32 v20, v9 offset:116
	s_waitcnt lgkmcnt(0)
	v_mul_f32_e32 v8, v128, v74
	v_fmac_f32_e32 v42, v66, v8
	v_fmac_f32_e32 v43, v67, v8
	v_fmac_f32_e32 v44, v68, v8
	v_fmac_f32_e32 v45, v69, v8
	v_fmac_f32_e32 v40, v70, v8
	v_fmac_f32_e32 v41, v71, v8
	v_fmac_f32_e32 v38, v72, v8
	v_fmac_f32_e32 v39, v73, v8
	v_mul_f32_e32 v8, v129, v20
	v_fmac_f32_e32 v42, v12, v8
	v_fmac_f32_e32 v43, v13, v8
	v_fmac_f32_e32 v44, v14, v8
	v_fmac_f32_e32 v45, v15, v8
	v_fmac_f32_e32 v40, v16, v8
	v_fmac_f32_e32 v41, v17, v8
	v_fmac_f32_e32 v38, v18, v8
	v_fmac_f32_e32 v39, v19, v8
	ds_read_b128 v[66:69], v7 offset:960
	ds_read_b128 v[70:73], v7 offset:976
	ds_read_b32 v74, v9 offset:120
	ds_read_b128 v[12:15], v7 offset:992
	ds_read_b128 v[16:19], v7 offset:1008
	ds_read_b32 v20, v9 offset:124
	s_waitcnt lgkmcnt(0)
	v_mul_f32_e32 v8, v130, v74
	v_fmac_f32_e32 v42, v66, v8
	v_fmac_f32_e32 v43, v67, v8
	v_fmac_f32_e32 v44, v68, v8
	v_fmac_f32_e32 v45, v69, v8
	v_fmac_f32_e32 v40, v70, v8
	v_fmac_f32_e32 v41, v71, v8
	v_fmac_f32_e32 v38, v72, v8
	v_fmac_f32_e32 v39, v73, v8
	v_mul_f32_e32 v8, v131, v20
	v_fmac_f32_e32 v42, v12, v8
	v_fmac_f32_e32 v43, v13, v8
	v_fmac_f32_e32 v44, v14, v8
	v_fmac_f32_e32 v45, v15, v8
	v_fmac_f32_e32 v40, v16, v8
	v_fmac_f32_e32 v41, v17, v8
	v_fmac_f32_e32 v38, v18, v8
	v_fmac_f32_e32 v39, v19, v8
	ds_read_b128 v[66:69], v7 offset:1024
	ds_read_b128 v[70:73], v7 offset:1040
	ds_read_b32 v74, v9 offset:128
	ds_read_b128 v[12:15], v7 offset:1056
	ds_read_b128 v[16:19], v7 offset:1072
	ds_read_b32 v20, v9 offset:132
	s_waitcnt lgkmcnt(0)
	v_mul_f32_e32 v8, v132, v74
	v_fmac_f32_e32 v42, v66, v8
	v_fmac_f32_e32 v43, v67, v8
	v_fmac_f32_e32 v44, v68, v8
	v_fmac_f32_e32 v45, v69, v8
	v_fmac_f32_e32 v40, v70, v8
	v_fmac_f32_e32 v41, v71, v8
	v_fmac_f32_e32 v38, v72, v8
	v_fmac_f32_e32 v39, v73, v8
	v_mul_f32_e32 v8, v133, v20
	v_fmac_f32_e32 v42, v12, v8
	v_fmac_f32_e32 v43, v13, v8
	v_fmac_f32_e32 v44, v14, v8
	v_fmac_f32_e32 v45, v15, v8
	v_fmac_f32_e32 v40, v16, v8
	v_fmac_f32_e32 v41, v17, v8
	v_fmac_f32_e32 v38, v18, v8
	v_fmac_f32_e32 v39, v19, v8
	ds_read_b128 v[66:69], v7 offset:1088
	ds_read_b128 v[70:73], v7 offset:1104
	ds_read_b32 v74, v9 offset:136
	ds_read_b128 v[12:15], v7 offset:1120
	ds_read_b128 v[16:19], v7 offset:1136
	ds_read_b32 v20, v9 offset:140
	s_waitcnt lgkmcnt(0)
	v_mul_f32_e32 v8, v134, v74
	v_fmac_f32_e32 v42, v66, v8
	v_fmac_f32_e32 v43, v67, v8
	v_fmac_f32_e32 v44, v68, v8
	v_fmac_f32_e32 v45, v69, v8
	v_fmac_f32_e32 v40, v70, v8
	v_fmac_f32_e32 v41, v71, v8
	v_fmac_f32_e32 v38, v72, v8
	v_fmac_f32_e32 v39, v73, v8
	v_mul_f32_e32 v8, v135, v20
	v_fmac_f32_e32 v42, v12, v8
	v_fmac_f32_e32 v43, v13, v8
	v_fmac_f32_e32 v44, v14, v8
	v_fmac_f32_e32 v45, v15, v8
	v_fmac_f32_e32 v40, v16, v8
	v_fmac_f32_e32 v41, v17, v8
	v_fmac_f32_e32 v38, v18, v8
	v_fmac_f32_e32 v39, v19, v8
	ds_read_b128 v[66:69], v7 offset:1152
	ds_read_b128 v[70:73], v7 offset:1168
	ds_read_b32 v74, v9 offset:144
	ds_read_b128 v[12:15], v7 offset:1184
	ds_read_b128 v[16:19], v7 offset:1200
	ds_read_b32 v20, v9 offset:148
	s_waitcnt lgkmcnt(0)
; __device__ __forceinline__ void weights_phase(int l, LAS unsigned char* lds, int vcu, int G, int wave, int lane) {
;     ...
; #pragma unroll 16
;             for (int e = 0; e < 128; ++e) { const float cf = wp[e] * ps[e]; a0 += cf * *(const f32x4*)(wb + (size_t)e * 1024); a1 += cf * *(const f32x4*)(wb + (size_t)e * 1024 + 4); }
	v_mul_f32_e32 v8, v136, v74
	v_fmac_f32_e32 v42, v66, v8
	v_fmac_f32_e32 v43, v67, v8
	v_fmac_f32_e32 v44, v68, v8
	v_fmac_f32_e32 v45, v69, v8
	v_fmac_f32_e32 v40, v70, v8
	v_fmac_f32_e32 v41, v71, v8
	v_fmac_f32_e32 v38, v72, v8
	v_fmac_f32_e32 v39, v73, v8
	v_mul_f32_e32 v8, v137, v20
	v_fmac_f32_e32 v42, v12, v8
	v_fmac_f32_e32 v43, v13, v8
	v_fmac_f32_e32 v44, v14, v8
	v_fmac_f32_e32 v45, v15, v8
	v_fmac_f32_e32 v40, v16, v8
	v_fmac_f32_e32 v41, v17, v8
	v_fmac_f32_e32 v38, v18, v8
	v_fmac_f32_e32 v39, v19, v8
	ds_read_b128 v[66:69], v7 offset:1216
	ds_read_b128 v[70:73], v7 offset:1232
	ds_read_b32 v74, v9 offset:152
	ds_read_b128 v[12:15], v7 offset:1248
	ds_read_b128 v[16:19], v7 offset:1264
	ds_read_b32 v20, v9 offset:156
	s_waitcnt lgkmcnt(0)
	v_mul_f32_e32 v8, v138, v74
	v_fmac_f32_e32 v42, v66, v8
	v_fmac_f32_e32 v43, v67, v8
	v_fmac_f32_e32 v44, v68, v8
	v_fmac_f32_e32 v45, v69, v8
	v_fmac_f32_e32 v40, v70, v8
	v_fmac_f32_e32 v41, v71, v8
	v_fmac_f32_e32 v38, v72, v8
	v_fmac_f32_e32 v39, v73, v8
	v_mul_f32_e32 v8, v139, v20
	v_fmac_f32_e32 v42, v12, v8
	v_fmac_f32_e32 v43, v13, v8
	v_fmac_f32_e32 v44, v14, v8
	v_fmac_f32_e32 v45, v15, v8
	v_fmac_f32_e32 v40, v16, v8
	v_fmac_f32_e32 v41, v17, v8
	v_fmac_f32_e32 v38, v18, v8
	v_fmac_f32_e32 v39, v19, v8
	ds_read_b128 v[66:69], v7 offset:1280
	ds_read_b128 v[70:73], v7 offset:1296
	ds_read_b32 v74, v9 offset:160
	ds_read_b128 v[12:15], v7 offset:1312
	ds_read_b128 v[16:19], v7 offset:1328
	ds_read_b32 v20, v9 offset:164
	s_waitcnt lgkmcnt(0)
	v_mul_f32_e32 v8, v140, v74
	v_fmac_f32_e32 v42, v66, v8
	v_fmac_f32_e32 v43, v67, v8
	v_fmac_f32_e32 v44, v68, v8
	v_fmac_f32_e32 v45, v69, v8
	v_fmac_f32_e32 v40, v70, v8
	v_fmac_f32_e32 v41, v71, v8
	v_fmac_f32_e32 v38, v72, v8
	v_fmac_f32_e32 v39, v73, v8
	v_mul_f32_e32 v8, v141, v20
	v_fmac_f32_e32 v42, v12, v8
	v_fmac_f32_e32 v43, v13, v8
	v_fmac_f32_e32 v44, v14, v8
	v_fmac_f32_e32 v45, v15, v8
	v_fmac_f32_e32 v40, v16, v8
	v_fmac_f32_e32 v41, v17, v8
	v_fmac_f32_e32 v38, v18, v8
	v_fmac_f32_e32 v39, v19, v8
	ds_read_b128 v[66:69], v7 offset:1344
	ds_read_b128 v[70:73], v7 offset:1360
	ds_read_b32 v74, v9 offset:168
	ds_read_b128 v[12:15], v7 offset:1376
	ds_read_b128 v[16:19], v7 offset:1392
	ds_read_b32 v20, v9 offset:172
	s_waitcnt lgkmcnt(0)
	v_mul_f32_e32 v8, v142, v74
	v_fmac_f32_e32 v42, v66, v8
	v_fmac_f32_e32 v43, v67, v8
	v_fmac_f32_e32 v44, v68, v8
	v_fmac_f32_e32 v45, v69, v8
	v_fmac_f32_e32 v40, v70, v8
	v_fmac_f32_e32 v41, v71, v8
	v_fmac_f32_e32 v38, v72, v8
	v_fmac_f32_e32 v39, v73, v8
	v_mul_f32_e32 v8, v143, v20
	v_fmac_f32_e32 v42, v12, v8
	v_fmac_f32_e32 v43, v13, v8
	v_fmac_f32_e32 v44, v14, v8
	v_fmac_f32_e32 v45, v15, v8
	v_fmac_f32_e32 v40, v16, v8
	v_fmac_f32_e32 v41, v17, v8
	v_fmac_f32_e32 v38, v18, v8
	v_fmac_f32_e32 v39, v19, v8
	ds_read_b128 v[66:69], v7 offset:1408
	ds_read_b128 v[70:73], v7 offset:1424
	ds_read_b32 v74, v9 offset:176
	ds_read_b128 v[12:15], v7 offset:1440
	ds_read_b128 v[16:19], v7 offset:1456
	ds_read_b32 v20, v9 offset:180
	s_waitcnt lgkmcnt(0)
	v_mul_f32_e32 v8, v144, v74
	v_fmac_f32_e32 v42, v66, v8
	v_fmac_f32_e32 v43, v67, v8
	v_fmac_f32_e32 v44, v68, v8
	v_fmac_f32_e32 v45, v69, v8
	v_fmac_f32_e32 v40, v70, v8
	v_fmac_f32_e32 v41, v71, v8
	v_fmac_f32_e32 v38, v72, v8
	v_fmac_f32_e32 v39, v73, v8
	v_mul_f32_e32 v8, v145, v20
	v_fmac_f32_e32 v42, v12, v8
	v_fmac_f32_e32 v43, v13, v8
	v_fmac_f32_e32 v44, v14, v8
	v_fmac_f32_e32 v45, v15, v8
	v_fmac_f32_e32 v40, v16, v8
	v_fmac_f32_e32 v41, v17, v8
	v_fmac_f32_e32 v38, v18, v8
	v_fmac_f32_e32 v39, v19, v8
	ds_read_b128 v[66:69], v7 offset:1472
	ds_read_b128 v[70:73], v7 offset:1488
	ds_read_b32 v74, v9 offset:184
	ds_read_b128 v[12:15], v7 offset:1504
	ds_read_b128 v[16:19], v7 offset:1520
	ds_read_b32 v20, v9 offset:188
	s_waitcnt lgkmcnt(0)
	v_mul_f32_e32 v8, v146, v74
	v_fmac_f32_e32 v42, v66, v8
	v_fmac_f32_e32 v43, v67, v8
	v_fmac_f32_e32 v44, v68, v8
	v_fmac_f32_e32 v45, v69, v8
	v_fmac_f32_e32 v40, v70, v8
	v_fmac_f32_e32 v41, v71, v8
	v_fmac_f32_e32 v38, v72, v8
	v_fmac_f32_e32 v39, v73, v8
	v_mul_f32_e32 v8, v147, v20
	v_fmac_f32_e32 v42, v12, v8
	v_fmac_f32_e32 v43, v13, v8
	v_fmac_f32_e32 v44, v14, v8
	v_fmac_f32_e32 v45, v15, v8
	v_fmac_f32_e32 v40, v16, v8
	v_fmac_f32_e32 v41, v17, v8
	v_fmac_f32_e32 v38, v18, v8
	v_fmac_f32_e32 v39, v19, v8
	ds_read_b128 v[66:69], v7 offset:1536
	ds_read_b128 v[70:73], v7 offset:1552
	ds_read_b32 v74, v9 offset:192
	ds_read_b128 v[12:15], v7 offset:1568
	ds_read_b128 v[16:19], v7 offset:1584
	ds_read_b32 v20, v9 offset:196
	s_waitcnt lgkmcnt(0)
	v_mul_f32_e32 v8, v148, v74
	v_fmac_f32_e32 v42, v66, v8
	v_fmac_f32_e32 v43, v67, v8
	v_fmac_f32_e32 v44, v68, v8
	v_fmac_f32_e32 v45, v69, v8
	v_fmac_f32_e32 v40, v70, v8
	v_fmac_f32_e32 v41, v71, v8
	v_fmac_f32_e32 v38, v72, v8
	v_fmac_f32_e32 v39, v73, v8
	v_mul_f32_e32 v8, v149, v20
	v_fmac_f32_e32 v42, v12, v8
	v_fmac_f32_e32 v43, v13, v8
	v_fmac_f32_e32 v44, v14, v8
	v_fmac_f32_e32 v45, v15, v8
	v_fmac_f32_e32 v40, v16, v8
	v_fmac_f32_e32 v41, v17, v8
	v_fmac_f32_e32 v38, v18, v8
	v_fmac_f32_e32 v39, v19, v8
	ds_read_b128 v[66:69], v7 offset:1600
	ds_read_b128 v[70:73], v7 offset:1616
	ds_read_b32 v74, v9 offset:200
	ds_read_b128 v[12:15], v7 offset:1632
	ds_read_b128 v[16:19], v7 offset:1648
	ds_read_b32 v20, v9 offset:204
	s_waitcnt lgkmcnt(0)
; __device__ __forceinline__ unsigned f2bf(float f) { unsigned u = __builtin_bit_cast(unsigned, f); return (u + 0x7fffu + ((u >> 16) & 1u)) >> 16; }
; __device__ __forceinline__ void weights_phase(int l, LAS unsigned char* lds, int vcu, int G, int wave, int lane) {
;     ...
;             for (int e = 0; e < 128; ++e) { const float cf = wp[e] * ps[e]; a0 += cf * *(const f32x4*)(wb + (size_t)e * 1024); a1 += cf * *(const f32x4*)(wb + (size_t)e * 1024 + 4); }
;             bf16* dst = WBR + (size_t)(1024 + cblk * 8) * 512 + g * 128 + ci;
;             dst[0 * 512] = (bf16)f2bf(a0.x); dst[1 * 512] = (bf16)f2bf(a0.y); dst[2 * 512] = (bf16)f2bf(a0.z); dst[3 * 512] = (bf16)f2bf(a0.w);
;             dst[4 * 512] = (bf16)f2bf(a1.x); dst[5 * 512] = (bf16)f2bf(a1.y); dst[6 * 512] = (bf16)f2bf(a1.z); dst[7 * 512] = (bf16)f2bf(a1.w);
	v_mul_f32_e32 v8, v150, v74
	v_fmac_f32_e32 v42, v66, v8
	v_fmac_f32_e32 v43, v67, v8
	v_fmac_f32_e32 v44, v68, v8
	v_fmac_f32_e32 v45, v69, v8
	v_fmac_f32_e32 v40, v70, v8
	v_fmac_f32_e32 v41, v71, v8
	v_fmac_f32_e32 v38, v72, v8
	v_fmac_f32_e32 v39, v73, v8
	v_mul_f32_e32 v8, v151, v20
	v_fmac_f32_e32 v42, v12, v8
	v_fmac_f32_e32 v43, v13, v8
	v_fmac_f32_e32 v44, v14, v8
	v_fmac_f32_e32 v45, v15, v8
	v_fmac_f32_e32 v40, v16, v8
	v_fmac_f32_e32 v41, v17, v8
	v_fmac_f32_e32 v38, v18, v8
	v_fmac_f32_e32 v39, v19, v8
	ds_read_b128 v[66:69], v7 offset:1664
	ds_read_b128 v[70:73], v7 offset:1680
	ds_read_b32 v74, v9 offset:208
	ds_read_b128 v[12:15], v7 offset:1696
	ds_read_b128 v[16:19], v7 offset:1712
	ds_read_b32 v20, v9 offset:212
	s_waitcnt lgkmcnt(0)
	v_mul_f32_e32 v8, v152, v74
	v_fmac_f32_e32 v42, v66, v8
	v_fmac_f32_e32 v43, v67, v8
	v_fmac_f32_e32 v44, v68, v8
	v_fmac_f32_e32 v45, v69, v8
	v_fmac_f32_e32 v40, v70, v8
	v_fmac_f32_e32 v41, v71, v8
	v_fmac_f32_e32 v38, v72, v8
	v_fmac_f32_e32 v39, v73, v8
	v_mul_f32_e32 v8, v153, v20
	v_fmac_f32_e32 v42, v12, v8
	v_fmac_f32_e32 v43, v13, v8
	v_fmac_f32_e32 v44, v14, v8
	v_fmac_f32_e32 v45, v15, v8
	v_fmac_f32_e32 v40, v16, v8
	v_fmac_f32_e32 v41, v17, v8
	v_fmac_f32_e32 v38, v18, v8
	v_fmac_f32_e32 v39, v19, v8
	ds_read_b128 v[66:69], v7 offset:1728
	ds_read_b128 v[70:73], v7 offset:1744
	ds_read_b32 v74, v9 offset:216
	ds_read_b128 v[12:15], v7 offset:1760
	ds_read_b128 v[16:19], v7 offset:1776
	ds_read_b32 v20, v9 offset:220
	s_waitcnt lgkmcnt(0)
	v_mul_f32_e32 v8, v154, v74
	v_fmac_f32_e32 v42, v66, v8
	v_fmac_f32_e32 v43, v67, v8
	v_fmac_f32_e32 v44, v68, v8
	v_fmac_f32_e32 v45, v69, v8
	v_fmac_f32_e32 v40, v70, v8
	v_fmac_f32_e32 v41, v71, v8
	v_fmac_f32_e32 v38, v72, v8
	v_fmac_f32_e32 v39, v73, v8
	v_mul_f32_e32 v8, v155, v20
	v_fmac_f32_e32 v42, v12, v8
	v_fmac_f32_e32 v43, v13, v8
	v_fmac_f32_e32 v44, v14, v8
	v_fmac_f32_e32 v45, v15, v8
	v_fmac_f32_e32 v40, v16, v8
	v_fmac_f32_e32 v41, v17, v8
	v_fmac_f32_e32 v38, v18, v8
	v_fmac_f32_e32 v39, v19, v8
	ds_read_b128 v[66:69], v7 offset:1792
	ds_read_b128 v[70:73], v7 offset:1808
	ds_read_b32 v74, v9 offset:224
	ds_read_b128 v[12:15], v7 offset:1824
	ds_read_b128 v[16:19], v7 offset:1840
	ds_read_b32 v20, v9 offset:228
	s_waitcnt lgkmcnt(0)
	v_mul_f32_e32 v8, v156, v74
	v_fmac_f32_e32 v42, v66, v8
	v_fmac_f32_e32 v43, v67, v8
	v_fmac_f32_e32 v44, v68, v8
	v_fmac_f32_e32 v45, v69, v8
	v_fmac_f32_e32 v40, v70, v8
	v_fmac_f32_e32 v41, v71, v8
	v_fmac_f32_e32 v38, v72, v8
	v_fmac_f32_e32 v39, v73, v8
	v_mul_f32_e32 v8, v157, v20
	v_fmac_f32_e32 v42, v12, v8
	v_fmac_f32_e32 v43, v13, v8
	v_fmac_f32_e32 v44, v14, v8
	v_fmac_f32_e32 v45, v15, v8
	v_fmac_f32_e32 v40, v16, v8
	v_fmac_f32_e32 v41, v17, v8
	v_fmac_f32_e32 v38, v18, v8
	v_fmac_f32_e32 v39, v19, v8
	ds_read_b128 v[66:69], v7 offset:1856
	ds_read_b128 v[70:73], v7 offset:1872
	ds_read_b32 v74, v9 offset:232
	ds_read_b128 v[12:15], v7 offset:1888
	ds_read_b128 v[16:19], v7 offset:1904
	ds_read_b32 v20, v9 offset:236
	s_waitcnt lgkmcnt(0)
	v_mul_f32_e32 v8, v158, v74
	v_fmac_f32_e32 v42, v66, v8
	v_fmac_f32_e32 v43, v67, v8
	v_fmac_f32_e32 v44, v68, v8
	v_fmac_f32_e32 v45, v69, v8
	v_fmac_f32_e32 v40, v70, v8
	v_fmac_f32_e32 v41, v71, v8
	v_fmac_f32_e32 v38, v72, v8
	v_fmac_f32_e32 v39, v73, v8
	v_mul_f32_e32 v8, v159, v20
	v_fmac_f32_e32 v42, v12, v8
	v_fmac_f32_e32 v43, v13, v8
	v_fmac_f32_e32 v44, v14, v8
	v_fmac_f32_e32 v45, v15, v8
	v_fmac_f32_e32 v40, v16, v8
	v_fmac_f32_e32 v41, v17, v8
	v_fmac_f32_e32 v38, v18, v8
	v_fmac_f32_e32 v39, v19, v8
	ds_read_b128 v[66:69], v7 offset:1920
	ds_read_b128 v[70:73], v7 offset:1936
	ds_read_b32 v74, v9 offset:240
	ds_read_b128 v[12:15], v7 offset:1952
	ds_read_b128 v[16:19], v7 offset:1968
	ds_read_b32 v20, v9 offset:244
	s_waitcnt lgkmcnt(0)
	v_mul_f32_e32 v8, v160, v74
	v_fmac_f32_e32 v42, v66, v8
	v_fmac_f32_e32 v43, v67, v8
	v_fmac_f32_e32 v44, v68, v8
	v_fmac_f32_e32 v45, v69, v8
	v_fmac_f32_e32 v40, v70, v8
	v_fmac_f32_e32 v41, v71, v8
	v_fmac_f32_e32 v38, v72, v8
	v_fmac_f32_e32 v39, v73, v8
	v_mul_f32_e32 v8, v161, v20
	v_fmac_f32_e32 v42, v12, v8
	v_fmac_f32_e32 v43, v13, v8
	v_fmac_f32_e32 v44, v14, v8
	v_fmac_f32_e32 v45, v15, v8
	v_fmac_f32_e32 v40, v16, v8
	v_fmac_f32_e32 v41, v17, v8
	v_fmac_f32_e32 v38, v18, v8
	v_fmac_f32_e32 v39, v19, v8
	ds_read_b128 v[66:69], v7 offset:1984
	ds_read_b128 v[70:73], v7 offset:2000
	ds_read_b32 v74, v9 offset:248
	ds_read_b128 v[12:15], v7 offset:2016
	ds_read_b128 v[16:19], v7 offset:2032
	ds_read_b32 v20, v9 offset:252
	s_waitcnt lgkmcnt(0)
	v_mul_f32_e32 v8, v162, v74
	v_fmac_f32_e32 v42, v66, v8
	v_fmac_f32_e32 v43, v67, v8
	v_fmac_f32_e32 v44, v68, v8
	v_fmac_f32_e32 v45, v69, v8
	v_fmac_f32_e32 v40, v70, v8
	v_fmac_f32_e32 v41, v71, v8
	v_fmac_f32_e32 v38, v72, v8
	v_fmac_f32_e32 v39, v73, v8
	v_mul_f32_e32 v8, v163, v20
	v_fmac_f32_e32 v42, v12, v8
	v_fmac_f32_e32 v43, v13, v8
	v_fmac_f32_e32 v44, v14, v8
	v_fmac_f32_e32 v45, v15, v8
	v_fmac_f32_e32 v40, v16, v8
	v_fmac_f32_e32 v41, v17, v8
	v_fmac_f32_e32 v38, v18, v8
	v_fmac_f32_e32 v39, v19, v8
	v_add_u32_e32 v7, 0x800, v7
	v_add_u32_e32 v9, 0x100, v9
	v_add_co_u32_e32 v10, vcc, 0x100, v10
	s_nop 1
	v_addc_co_u32_e32 v11, vcc, 0, v11, vcc
	s_add_u32 s17, s17, 1
	s_cmp_lt_u32 s17, 2
	s_cbranch_scc1 .Lweff_half_b
	s_lshr_b32 s0, s3, 1
	v_and_or_b32 v0, s0, 64, v27
	s_lshl_b32 s0, s3, 13
	s_and_b32 s0, s0, 0xfe000
	s_add_u32 s12, s6, s0
	s_addc_u32 s13, s7, 0
	s_lshl_b64 s[0:1], s[10:11], 1
	s_add_u32 s0, s12, s0
	s_addc_u32 s1, s13, s1
	v_lshlrev_b32_e32 v0, 1, v0
	v_lshl_add_u64 v[2:3], s[0:1], 0, v[0:1]
	s_mov_b64 s[0:1], 0x100000
	v_lshl_add_u64 v[4:5], v[2:3], 0, s[0:1]
	s_mov_b32 s0, 0x101000
	v_bfe_u32 v0, v42, 16, 1
	v_add_co_u32_e32 v2, vcc, s0, v2
	v_add3_u32 v0, v42, v0, s58
	s_nop 0
	v_addc_co_u32_e32 v3, vcc, 0, v3, vcc
	global_store_short_d16_hi v[2:3], v0, off offset:-4096
	v_bfe_u32 v0, v43, 16, 1
	v_add3_u32 v0, v43, v0, s58
	global_store_short_d16_hi v[4:5], v0, off offset:1024
	v_bfe_u32 v0, v44, 16, 1
	v_add3_u32 v0, v44, v0, s58
	global_store_short_d16_hi v[4:5], v0, off offset:2048
	v_bfe_u32 v0, v45, 16, 1
	v_add3_u32 v0, v45, v0, s58
	global_store_short_d16_hi v[4:5], v0, off offset:3072
	v_bfe_u32 v0, v40, 16, 1
	v_add3_u32 v0, v40, v0, s58
	global_store_short_d16_hi v[2:3], v0, off
	v_bfe_u32 v0, v41, 16, 1
	v_add3_u32 v0, v41, v0, s58
	global_store_short_d16_hi v[2:3], v0, off offset:1024
	v_bfe_u32 v0, v38, 16, 1
	v_add3_u32 v0, v38, v0, s58
	global_store_short_d16_hi v[2:3], v0, off offset:2048
	v_bfe_u32 v0, v39, 16, 1
	v_add3_u32 v0, v39, v0, s58
	global_store_short_d16_hi v[2:3], v0, off offset:3072
	s_branch .LBB0_184
